# boundary-token conditional loads in cout/prep issued together with one wait; EpiResid epilogue loads (gate + residual) for a row issued together into fresh registers
# speedup vs baseline: 1.0666x; 1.0138x over previous
.LBB0_246:
	v_mov_b64_e32 v[14:15], s[80:81]
	v_mad_i64_i32 v[18:19], s[0:1], v2, s17, v[14:15]
	v_mov_b32_e32 v11, v0
	v_lshl_add_u64 v[16:17], v[18:19], 0, v[10:11]
	global_load_ushort v20, v[16:17], off
	global_load_ushort v15, v[16:17], off offset:128
	global_load_ushort v64, v[16:17], off offset:256
	global_load_ushort v63, v[16:17], off offset:384
	global_load_ushort v62, v[16:17], off offset:512
	global_load_ushort v61, v[16:17], off offset:640
	global_load_ushort v60, v[16:17], off offset:768
	global_load_ushort v59, v[16:17], off offset:896
	global_load_ushort v58, v[16:17], off offset:1024
	global_load_ushort v57, v[16:17], off offset:1152
	global_load_ushort v55, v[16:17], off offset:1536
	global_load_ushort v56, v[16:17], off offset:1664
	global_load_ushort v54, v[16:17], off offset:1792
	global_load_ushort v53, v[16:17], off offset:1920
	global_load_ushort v52, v[16:17], off offset:2048
	global_load_ushort v51, v[16:17], off offset:2176
	v_mov_b32_e32 v13, v0
	v_add_co_u32_e32 v22, vcc, 0x1000, v16
	v_lshl_add_u64 v[18:19], v[18:19], 0, v[12:13]
	s_nop 0
	v_addc_co_u32_e32 v23, vcc, 0, v17, vcc
	global_load_ushort v49, v[16:17], off offset:2304
	global_load_ushort v50, v[16:17], off offset:2432
	global_load_ushort v48, v[16:17], off offset:2560
	global_load_ushort v47, v[16:17], off offset:2688
	global_load_ushort v46, v[18:19], off offset:2816
	global_load_ushort v3, v[22:23], off offset:2368
	s_mov_b32 s0, 0x38e38e39
	v_mul_hi_i32 v11, v2, s0
	v_lshrrev_b32_e32 v13, 31, v11
	v_ashrrev_i32_e32 v11, 9, v11
	v_add_u32_e32 v45, v11, v13
	v_mad_i32_i24 v14, v45, s53, v2
	v_cmp_lt_i32_e64 s[46:47], s10, v14
	v_mov_b32_e32 v13, 0
	s_nop 0
	v_cndmask_b32_e64 v11, 0, v239, s[46:47]
	v_cmp_gt_i32_e64 s[48:49], v14, v11
	v_mov_b32_e32 v11, 0
	s_and_saveexec_b64 s[6:7], s[48:49]
	s_cbranch_execz .LBB0_248
	global_load_ushort v11, v[16:17], off offset:-3520
.LBB0_248:
	s_or_b64 exec, exec, s[6:7]
	v_cndmask_b32_e64 v18, v240, v241, s[46:47]
	v_cmp_lt_i32_e64 s[50:51], v14, v18
	s_and_saveexec_b64 s[6:7], s[50:51]
	s_cbranch_execz .LBB0_250
	v_add_co_u32_e32 v18, vcc, 0x4000, v16
	s_nop 1
	v_addc_co_u32_e32 v19, vcc, 0, v17, vcc
	global_load_ushort v13, v[18:19], off offset:64
.LBB0_250:
	s_or_b64 exec, exec, s[6:7]
	v_lshl_add_u64 v[18:19], v[16:17], 0, s[24:25]
	v_add_co_u32_e32 v22, vcc, 0x1000, v18
	v_mov_b32_e32 v44, 0
	s_nop 0
	v_addc_co_u32_e32 v23, vcc, 0, v19, vcc
	global_load_ushort v42, v[22:23], off offset:2368
	v_mov_b32_e32 v43, 0
	s_and_saveexec_b64 s[6:7], s[48:49]
	s_cbranch_execz .LBB0_252
	s_waitcnt lgkmcnt(0)
	global_load_ushort v43, v[16:17], off offset:-3392
.LBB0_252:
	s_or_b64 exec, exec, s[6:7]
	s_and_saveexec_b64 s[6:7], s[50:51]
	s_cbranch_execz .LBB0_254
	v_add_co_u32_e32 v18, vcc, 0x4000, v18
	s_nop 1
	v_addc_co_u32_e32 v19, vcc, 0, v19, vcc
	global_load_ushort v44, v[18:19], off offset:64
.LBB0_254:
	s_or_b64 exec, exec, s[6:7]
	s_waitcnt vmcnt(0)
	v_lshlrev_b32_e32 v11, 16, v11
	v_lshlrev_b32_e32 v13, 16, v13
	v_lshlrev_b32_e32 v43, 16, v43
	v_lshlrev_b32_e32 v44, 16, v44
	v_mov_b32_e32 v19, 0
	v_mov_b32_e32 v18, 1.0
	v_mov_b32_e32 v22, 1.0
	v_mov_b32_e32 v23, 0
	s_and_saveexec_b64 s[6:7], s[46:47]
	s_cbranch_execz .LBB0_256
	v_add_u32_e32 v18, 0x700, v14
	v_bfe_u32 v18, v18, 6, 5
	v_and_b32_e32 v19, 63, v2
	s_waitcnt lgkmcnt(0)
	v_cndmask_b32_e64 v21, v19, v18, s[38:39]
	v_readlane_b32 s0, v254, 0
	v_lshl_or_b32 v21, v21, 7, v40
	v_readlane_b32 s1, v254, 1
	v_cndmask_b32_e64 v18, v19, v18, s[40:41]
	v_lshl_or_b32 v18, v18, 6, v41
	s_nop 2
	global_load_dwordx2 v[22:23], v21, s[0:1]
	v_readlane_b32 s0, v252, 24
	v_readlane_b32 s1, v252, 25
	s_nop 4
	global_load_dwordx2 v[18:19], v18, s[0:1]

.LBB0_747:
	s_or_b64 exec, exec, s[6:7]
	s_waitcnt vmcnt(0)
	v_lshlrev_b32_e32 v96, 16, v96
	v_lshlrev_b32_e32 v95, 16, v95
	v_lshlrev_b32_e32 v11, 16, v11
	v_lshlrev_b32_e32 v9, 16, v9
	v_lshlrev_b32_e32 v63, 16, v63
	v_lshlrev_b32_e32 v62, 16, v62
	v_lshlrev_b32_e32 v69, 16, v69
	v_lshlrev_b32_e32 v68, 16, v68
	v_lshlrev_b32_e32 v75, 16, v75
	v_lshlrev_b32_e32 v74, 16, v74
	v_lshlrev_b32_e32 v81, 16, v81
	v_lshlrev_b32_e32 v80, 16, v80
	v_lshlrev_b32_e32 v87, 16, v87
	v_lshlrev_b32_e32 v86, 16, v86
	v_lshlrev_b32_e32 v92, 16, v92
	v_lshlrev_b32_e32 v91, 16, v91
	global_load_dwordx2 v[100:101], v[46:47], off offset:56
	s_waitcnt vmcnt(19)
	v_add_f32_e32 v54, v54, v55
	global_load_dword v55, v[24:25], off
	s_waitcnt vmcnt(6)
	v_add_f32_e32 v48, v60, v61
	v_add_f32_e32 v56, v56, v57
	v_add_f32_e32 v51, v50, v51
	v_lshlrev_b32_e32 v47, 16, v93
	v_lshlrev_b32_e32 v57, 16, v94
	v_add_f32_e32 v50, v96, v95
	global_load_dword v60, v[20:21], off
	global_load_dword v61, v[20:21], off offset:256
	global_load_dword v93, v[22:23], off
	global_load_dword v94, v[22:23], off offset:256
	global_load_dword v95, v[26:27], off
	v_add_f32_e32 v49, v58, v59
	v_lshlrev_b32_e32 v46, 16, v97
	v_lshlrev_b32_e32 v58, 16, v98
	v_lshlrev_b32_e32 v59, 16, v99
	v_add_f32_e32 v96, v46, v47
	v_add_f32_e32 v98, v58, v59
	v_fma_f32 v97, v50, 0.5, -v57
	v_add_f32_dpp v46, v96, v96 quad_perm:[1,0,3,2] row_mask:0xf bank_mask:0xf bound_ctrl:1
	v_add_f32_dpp v47, v98, v98 quad_perm:[1,0,3,2] row_mask:0xf bank_mask:0xf bound_ctrl:1
	s_mov_b32 s0, 0x3a27c5ac
	v_add_f32_dpp v46, v46, v46 quad_perm:[2,3,0,1] row_mask:0xf bank_mask:0xf bound_ctrl:1
	v_add_f32_dpp v47, v47, v47 quad_perm:[2,3,0,1] row_mask:0xf bank_mask:0xf bound_ctrl:1
	v_add_f32_e32 v52, v52, v53
	v_add_f32_dpp v46, v46, v46 row_half_mirror row_mask:0xf bank_mask:0xf bound_ctrl:1
	v_add_f32_dpp v47, v47, v47 row_half_mirror row_mask:0xf bank_mask:0xf bound_ctrl:1
	v_add_f32_e32 v53, v44, v45
	v_add_f32_dpp v46, v46, v46 row_mirror row_mask:0xf bank_mask:0xf bound_ctrl:1
	v_add_f32_dpp v47, v47, v47 row_mirror row_mask:0xf bank_mask:0xf bound_ctrl:1
	v_mov_b32_e32 v50, v46
	v_mov_b32_e32 v58, v47
	s_nop 0
	v_permlane16_swap_b32_e32 v46, v50
	v_permlane16_swap_b32_e32 v47, v58
	v_add_f32_e32 v46, v46, v50
	v_add_f32_e32 v47, v47, v58
	v_mov_b32_e32 v50, v46
	v_mov_b32_e32 v58, v47
	s_nop 0
	v_permlane32_swap_b32_e32 v46, v50
	v_permlane32_swap_b32_e32 v47, v58
	v_add_f32_e32 v46, v46, v50
	v_add_f32_e32 v47, v47, v58
	v_fmac_f32_e32 v96, 0xbc800000, v46
	v_fmac_f32_e32 v98, 0xbc800000, v47
	v_mul_f32_e32 v46, v96, v96
	v_mul_f32_e32 v47, v98, v98
	v_mov_b64_e32 v[44:45], s[0:1]
	v_mov_b32_dpp v46, v46 quad_perm:[1,0,3,2] row_mask:0xf bank_mask:0xf bound_ctrl:1
	v_mov_b32_dpp v47, v47 quad_perm:[1,0,3,2] row_mask:0xf bank_mask:0xf bound_ctrl:1
	v_fmac_f32_e32 v46, v96, v96
	v_fmac_f32_e32 v47, v98, v98
	s_mov_b32 s2, 0x3c800000
	v_add_f32_dpp v46, v46, v46 quad_perm:[2,3,0,1] row_mask:0xf bank_mask:0xf bound_ctrl:1
	v_add_f32_dpp v47, v47, v47 quad_perm:[2,3,0,1] row_mask:0xf bank_mask:0xf bound_ctrl:1
	s_mov_b32 s0, 0x800000
	v_add_f32_dpp v46, v46, v46 row_half_mirror row_mask:0xf bank_mask:0xf bound_ctrl:1
	v_add_f32_dpp v47, v47, v47 row_half_mirror row_mask:0xf bank_mask:0xf bound_ctrl:1
	v_lshlrev_b32_e32 v1, 16, v1
	v_add_f32_dpp v46, v46, v46 row_mirror row_mask:0xf bank_mask:0xf bound_ctrl:1
	v_add_f32_dpp v50, v47, v47 row_mirror row_mask:0xf bank_mask:0xf bound_ctrl:1
	v_mov_b32_e32 v47, v46
	v_mov_b32_e32 v58, v50
	s_nop 0
	v_permlane16_swap_b32_e32 v46, v47
	v_permlane16_swap_b32_e32 v50, v58
	v_add_f32_e32 v47, v46, v47
	v_add_f32_e32 v46, v50, v58
	v_mov_b32_e32 v59, v47
	v_mov_b32_e32 v58, v46
	s_nop 0
	v_permlane32_swap_b32_e32 v47, v59
	v_permlane32_swap_b32_e32 v46, v58
	v_pk_add_f32 v[46:47], v[46:47], v[58:59]
	s_waitcnt vmcnt(6)
	v_add_f32_e32 v50, v100, v101
	v_pk_fma_f32 v[46:47], v[46:47], s[2:3], v[44:45] op_sel_hi:[1,0,0]
	global_load_dword v99, v[28:29], off
	global_load_dword v100, v[30:31], off
	global_load_dword v101, v[32:33], off
	global_load_dword v102, v[34:35], off
	global_load_dword v103, v[36:37], off
	global_load_dword v104, v[38:39], off
	v_mul_f32_e32 v58, 0x4b800000, v47
	v_cmp_gt_f32_e32 vcc, s0, v47
	s_waitcnt vmcnt(11)
	v_fmac_f32_e32 v57, v97, v55
	v_cndmask_b32_e32 v47, v47, v58, vcc
	v_rsq_f32_e32 v47, v47
	s_nop 0
	v_mul_f32_e32 v55, 0x45800000, v47
	v_cndmask_b32_e32 v47, v47, v55, vcc
	v_mul_f32_e32 v47, v96, v47
	global_load_dword v55, v[20:21], off offset:512
	global_load_dword v96, v[20:21], off offset:768
	global_load_dword v97, v[20:21], off offset:1024
	global_load_dword v105, v[20:21], off offset:1280
	global_load_dword v106, v[20:21], off offset:1536
	global_load_dword v107, v[20:21], off offset:1792
	global_load_dword v108, v[22:23], off offset:512
	global_load_dword v109, v[22:23], off offset:768
	global_load_dword v110, v[22:23], off offset:1024
	global_load_dword v111, v[22:23], off offset:1280
	global_load_dword v112, v[22:23], off offset:1536
	global_load_dword v113, v[22:23], off offset:1792
	s_waitcnt vmcnt(20)
	v_fmac_f32_e32 v93, v60, v47
	v_mul_f32_e32 v47, 0x4b800000, v46
	v_cmp_gt_f32_e32 vcc, s0, v46
	v_fmac_f32_e32 v93, v53, v57
	v_mul_f32_e32 v1, v93, v1
	v_cndmask_b32_e32 v46, v46, v47, vcc
	v_rsq_f32_e32 v46, v46
	v_bfe_u32 v47, v1, 16, 1
	v_add3_u32 v1, v1, v47, s19
	global_store_short_d16_hi v[42:43], v1, off offset:2880
	v_mul_f32_e32 v1, 0x45800000, v46
	v_cndmask_b32_e32 v1, v46, v1, vcc
	v_mul_f32_e32 v1, v98, v1
	s_waitcnt vmcnt(20)
	v_fmac_f32_e32 v94, v61, v1
	v_lshlrev_b32_e32 v1, 16, v5
	v_add_f32_e32 v5, v11, v9
	v_fma_f32 v5, v5, 0.5, -v1
	s_waitcnt vmcnt(19)
	v_fmac_f32_e32 v1, v5, v95
	v_fmac_f32_e32 v94, v51, v1
	v_lshlrev_b32_e32 v1, 16, v3
	v_mul_f32_e32 v1, v94, v1
	v_bfe_u32 v3, v1, 16, 1
	v_add3_u32 v1, v1, v3, s19
	global_store_short_d16_hi v[42:43], v1, off offset:3008
	v_lshlrev_b32_e32 v1, 16, v13
	v_lshlrev_b32_e32 v3, 16, v15
	v_lshlrev_b32_e32 v9, 16, v66
	v_lshlrev_b32_e32 v11, 16, v67
	v_add_f32_e32 v1, v1, v3
	v_add_f32_e32 v9, v9, v11
	s_nop 0
	v_add_f32_dpp v3, v1, v1 quad_perm:[1,0,3,2] row_mask:0xf bank_mask:0xf bound_ctrl:1
	v_add_f32_dpp v11, v9, v9 quad_perm:[1,0,3,2] row_mask:0xf bank_mask:0xf bound_ctrl:1
	s_nop 0
	v_add_f32_dpp v3, v3, v3 quad_perm:[2,3,0,1] row_mask:0xf bank_mask:0xf bound_ctrl:1
	v_add_f32_dpp v11, v11, v11 quad_perm:[2,3,0,1] row_mask:0xf bank_mask:0xf bound_ctrl:1
	s_nop 0
	v_add_f32_dpp v3, v3, v3 row_half_mirror row_mask:0xf bank_mask:0xf bound_ctrl:1
	v_add_f32_dpp v11, v11, v11 row_half_mirror row_mask:0xf bank_mask:0xf bound_ctrl:1
	s_nop 0
	v_add_f32_dpp v3, v3, v3 row_mirror row_mask:0xf bank_mask:0xf bound_ctrl:1
	v_add_f32_dpp v11, v11, v11 row_mirror row_mask:0xf bank_mask:0xf bound_ctrl:1
	v_mov_b32_e32 v5, v3
	v_mov_b32_e32 v13, v11
	s_nop 0
	v_permlane16_swap_b32_e32 v3, v5
	v_permlane16_swap_b32_e32 v11, v13
	v_add_f32_e32 v3, v3, v5
	v_add_f32_e32 v11, v11, v13
	v_mov_b32_e32 v5, v3
	v_mov_b32_e32 v13, v11
	s_nop 0
	v_permlane32_swap_b32_e32 v3, v5
	v_permlane32_swap_b32_e32 v11, v13
	v_add_f32_e32 v3, v3, v5
	v_add_f32_e32 v11, v11, v13
	v_fmac_f32_e32 v1, 0xbc800000, v3
	v_fmac_f32_e32 v9, 0xbc800000, v11
	v_mul_f32_e32 v3, v1, v1
	v_mul_f32_e32 v11, v9, v9
	s_nop 0
	v_mov_b32_dpp v3, v3 quad_perm:[1,0,3,2] row_mask:0xf bank_mask:0xf bound_ctrl:1
	v_mov_b32_dpp v11, v11 quad_perm:[1,0,3,2] row_mask:0xf bank_mask:0xf bound_ctrl:1
	v_fmac_f32_e32 v3, v1, v1
	v_fmac_f32_e32 v11, v9, v9
	s_nop 0
	v_add_f32_dpp v3, v3, v3 quad_perm:[2,3,0,1] row_mask:0xf bank_mask:0xf bound_ctrl:1
	v_add_f32_dpp v11, v11, v11 quad_perm:[2,3,0,1] row_mask:0xf bank_mask:0xf bound_ctrl:1
	s_nop 0
	v_add_f32_dpp v3, v3, v3 row_half_mirror row_mask:0xf bank_mask:0xf bound_ctrl:1
	v_add_f32_dpp v11, v11, v11 row_half_mirror row_mask:0xf bank_mask:0xf bound_ctrl:1
	s_nop 0
	v_add_f32_dpp v3, v3, v3 row_mirror row_mask:0xf bank_mask:0xf bound_ctrl:1
	v_add_f32_dpp v11, v11, v11 row_mirror row_mask:0xf bank_mask:0xf bound_ctrl:1
	v_mov_b32_e32 v5, v3
	v_mov_b32_e32 v13, v11
	s_nop 0
	v_permlane16_swap_b32_e32 v3, v5
	v_permlane16_swap_b32_e32 v11, v13
	v_add_f32_e32 v47, v3, v5
	v_add_f32_e32 v46, v11, v13
	v_mov_b32_e32 v59, v47
	v_mov_b32_e32 v58, v46
	s_nop 0
	v_permlane32_swap_b32_e32 v47, v59
	v_permlane32_swap_b32_e32 v46, v58
	v_pk_add_f32 v[46:47], v[46:47], v[58:59]
	v_lshlrev_b32_e32 v3, 16, v17
	v_pk_fma_f32 v[46:47], v[46:47], s[2:3], v[44:45] op_sel_hi:[1,0,0]
	v_add_f32_e32 v5, v63, v62
	v_mul_f32_e32 v11, 0x4b800000, v47
	v_cmp_gt_f32_e32 vcc, s0, v47
	v_fma_f32 v5, v5, 0.5, -v3
	s_waitcnt vmcnt(19)
	v_fmac_f32_e32 v3, v5, v99
	v_cndmask_b32_e32 v11, v47, v11, vcc
	v_rsq_f32_e32 v11, v11
	v_lshlrev_b32_e32 v5, 16, v7
	v_mul_f32_e32 v7, 0x45800000, v11
	v_cndmask_b32_e32 v7, v11, v7, vcc
	v_mul_f32_e32 v1, v1, v7
	s_waitcnt vmcnt(7)
	v_fmac_f32_e32 v108, v55, v1
	v_fmac_f32_e32 v108, v52, v3
	v_mul_f32_e32 v3, 0x4b800000, v46
	v_cmp_gt_f32_e32 vcc, s0, v46
	v_mul_f32_e32 v1, v108, v5
	v_bfe_u32 v5, v1, 16, 1
	v_cndmask_b32_e32 v3, v46, v3, vcc
	v_rsq_f32_e32 v3, v3
	v_add3_u32 v1, v1, v5, s19
	global_store_short_d16_hi v[42:43], v1, off offset:3136
	v_lshlrev_b32_e32 v7, 16, v78
	v_mul_f32_e32 v1, 0x45800000, v3
	v_cndmask_b32_e32 v1, v3, v1, vcc
	v_mul_f32_e32 v1, v9, v1
	s_waitcnt vmcnt(7)
	v_fmac_f32_e32 v109, v96, v1
	v_lshlrev_b32_e32 v1, 16, v64
	v_add_f32_e32 v3, v69, v68
	v_fma_f32 v3, v3, 0.5, -v1
	v_fmac_f32_e32 v1, v3, v100
	v_fmac_f32_e32 v109, v54, v1
	v_lshlrev_b32_e32 v1, 16, v19
	v_mul_f32_e32 v1, v109, v1
	v_bfe_u32 v3, v1, 16, 1
	v_add3_u32 v1, v1, v3, s19
	global_store_short_d16_hi v[42:43], v1, off offset:3264
	v_lshlrev_b32_e32 v1, 16, v70
	v_lshlrev_b32_e32 v3, 16, v71
	v_lshlrev_b32_e32 v9, 16, v79
	v_add_f32_e32 v1, v1, v3
	v_add_f32_e32 v7, v7, v9
	s_nop 0
	v_add_f32_dpp v3, v1, v1 quad_perm:[1,0,3,2] row_mask:0xf bank_mask:0xf bound_ctrl:1
	v_add_f32_dpp v9, v7, v7 quad_perm:[1,0,3,2] row_mask:0xf bank_mask:0xf bound_ctrl:1
	s_nop 0
	v_add_f32_dpp v3, v3, v3 quad_perm:[2,3,0,1] row_mask:0xf bank_mask:0xf bound_ctrl:1
	v_add_f32_dpp v9, v9, v9 quad_perm:[2,3,0,1] row_mask:0xf bank_mask:0xf bound_ctrl:1
	s_nop 0
	v_add_f32_dpp v3, v3, v3 row_half_mirror row_mask:0xf bank_mask:0xf bound_ctrl:1
	v_add_f32_dpp v9, v9, v9 row_half_mirror row_mask:0xf bank_mask:0xf bound_ctrl:1
	s_nop 0
	v_add_f32_dpp v3, v3, v3 row_mirror row_mask:0xf bank_mask:0xf bound_ctrl:1
	v_add_f32_dpp v9, v9, v9 row_mirror row_mask:0xf bank_mask:0xf bound_ctrl:1
	v_mov_b32_e32 v5, v3
	v_mov_b32_e32 v11, v9
	s_nop 0
	v_permlane16_swap_b32_e32 v3, v5
	v_permlane16_swap_b32_e32 v9, v11
	v_add_f32_e32 v3, v3, v5
	v_add_f32_e32 v9, v9, v11
	v_mov_b32_e32 v5, v3
	v_mov_b32_e32 v11, v9
	s_nop 0
	v_permlane32_swap_b32_e32 v3, v5
	v_permlane32_swap_b32_e32 v9, v11
	v_add_f32_e32 v3, v3, v5
	v_add_f32_e32 v9, v9, v11
	v_fmac_f32_e32 v1, 0xbc800000, v3
	v_fmac_f32_e32 v7, 0xbc800000, v9
	v_mul_f32_e32 v3, v1, v1
	v_mul_f32_e32 v9, v7, v7
	s_nop 0
	v_mov_b32_dpp v3, v3 quad_perm:[1,0,3,2] row_mask:0xf bank_mask:0xf bound_ctrl:1
	v_mov_b32_dpp v9, v9 quad_perm:[1,0,3,2] row_mask:0xf bank_mask:0xf bound_ctrl:1
	v_fmac_f32_e32 v3, v1, v1
	v_fmac_f32_e32 v9, v7, v7
	s_nop 0
	v_add_f32_dpp v3, v3, v3 quad_perm:[2,3,0,1] row_mask:0xf bank_mask:0xf bound_ctrl:1
	v_add_f32_dpp v9, v9, v9 quad_perm:[2,3,0,1] row_mask:0xf bank_mask:0xf bound_ctrl:1
	s_nop 0
	v_add_f32_dpp v3, v3, v3 row_half_mirror row_mask:0xf bank_mask:0xf bound_ctrl:1
	v_add_f32_dpp v9, v9, v9 row_half_mirror row_mask:0xf bank_mask:0xf bound_ctrl:1
	s_nop 0
	v_add_f32_dpp v3, v3, v3 row_mirror row_mask:0xf bank_mask:0xf bound_ctrl:1
	v_add_f32_dpp v9, v9, v9 row_mirror row_mask:0xf bank_mask:0xf bound_ctrl:1
	v_mov_b32_e32 v5, v3
	v_mov_b32_e32 v11, v9
	s_nop 0
	v_permlane16_swap_b32_e32 v3, v5
	v_permlane16_swap_b32_e32 v9, v11
	v_add_f32_e32 v47, v3, v5
	v_add_f32_e32 v46, v9, v11
	v_mov_b32_e32 v53, v47
	v_mov_b32_e32 v52, v46
	s_nop 0
	v_permlane32_swap_b32_e32 v47, v53
	v_permlane32_swap_b32_e32 v46, v52
	v_pk_add_f32 v[46:47], v[46:47], v[52:53]
	v_lshlrev_b32_e32 v3, 16, v72
	v_pk_fma_f32 v[46:47], v[46:47], s[2:3], v[44:45] op_sel_hi:[1,0,0]
	v_add_f32_e32 v5, v75, v74
	v_mul_f32_e32 v9, 0x4b800000, v47
	v_cmp_gt_f32_e32 vcc, s0, v47
	v_fma_f32 v5, v5, 0.5, -v3
	v_fmac_f32_e32 v3, v5, v101
	v_cndmask_b32_e32 v9, v47, v9, vcc
	v_rsq_f32_e32 v9, v9
	v_lshlrev_b32_e32 v5, 16, v65
	v_mul_f32_e32 v11, 0x45800000, v9
	v_cndmask_b32_e32 v9, v9, v11, vcc
	v_mul_f32_e32 v1, v1, v9
	s_waitcnt vmcnt(7)
	v_fmac_f32_e32 v110, v97, v1
	v_fmac_f32_e32 v110, v56, v3
	v_mul_f32_e32 v3, 0x4b800000, v46
	v_cmp_gt_f32_e32 vcc, s0, v46
	v_mul_f32_e32 v1, v110, v5
	v_bfe_u32 v5, v1, 16, 1
	v_cndmask_b32_e32 v3, v46, v3, vcc
	v_rsq_f32_e32 v3, v3
	v_add3_u32 v1, v1, v5, s19
	global_store_short_d16_hi v[42:43], v1, off offset:3392
	v_lshlrev_b32_e32 v9, 16, v90
	v_mul_f32_e32 v1, 0x45800000, v3
	v_cndmask_b32_e32 v1, v3, v1, vcc
	v_mul_f32_e32 v1, v7, v1
	s_waitcnt vmcnt(7)
	v_fmac_f32_e32 v111, v105, v1
	v_lshlrev_b32_e32 v1, 16, v77
	v_add_f32_e32 v3, v81, v80
	v_fma_f32 v3, v3, 0.5, -v1
	v_fmac_f32_e32 v1, v3, v102
	v_fmac_f32_e32 v111, v49, v1
	v_lshlrev_b32_e32 v1, 16, v73
	v_mul_f32_e32 v1, v111, v1
	v_bfe_u32 v3, v1, 16, 1
	v_add3_u32 v1, v1, v3, s19
	global_store_short_d16_hi v[42:43], v1, off offset:3520
	v_lshlrev_b32_e32 v1, 16, v82
	v_lshlrev_b32_e32 v3, 16, v83
	v_lshlrev_b32_e32 v7, 16, v89
	v_add_f32_e32 v1, v1, v3
	v_add_f32_e32 v7, v7, v9
	s_nop 0
	v_add_f32_dpp v3, v1, v1 quad_perm:[1,0,3,2] row_mask:0xf bank_mask:0xf bound_ctrl:1
	v_add_f32_dpp v9, v7, v7 quad_perm:[1,0,3,2] row_mask:0xf bank_mask:0xf bound_ctrl:1
	s_nop 0
	v_add_f32_dpp v3, v3, v3 quad_perm:[2,3,0,1] row_mask:0xf bank_mask:0xf bound_ctrl:1
	v_add_f32_dpp v9, v9, v9 quad_perm:[2,3,0,1] row_mask:0xf bank_mask:0xf bound_ctrl:1
	s_nop 0
	v_add_f32_dpp v3, v3, v3 row_half_mirror row_mask:0xf bank_mask:0xf bound_ctrl:1
	v_add_f32_dpp v9, v9, v9 row_half_mirror row_mask:0xf bank_mask:0xf bound_ctrl:1
	s_nop 0
	v_add_f32_dpp v3, v3, v3 row_mirror row_mask:0xf bank_mask:0xf bound_ctrl:1
	v_add_f32_dpp v9, v9, v9 row_mirror row_mask:0xf bank_mask:0xf bound_ctrl:1
	v_mov_b32_e32 v5, v3
	v_mov_b32_e32 v11, v9
	s_nop 0
	v_permlane16_swap_b32_e32 v3, v5
	v_permlane16_swap_b32_e32 v9, v11
	v_add_f32_e32 v3, v3, v5
	v_add_f32_e32 v9, v9, v11
	v_mov_b32_e32 v5, v3
	v_mov_b32_e32 v11, v9
	s_nop 0
	v_permlane32_swap_b32_e32 v3, v5
	v_permlane32_swap_b32_e32 v9, v11
	v_add_f32_e32 v3, v3, v5
	v_add_f32_e32 v9, v9, v11
	v_fmac_f32_e32 v1, 0xbc800000, v3
	v_fmac_f32_e32 v7, 0xbc800000, v9
	v_mul_f32_e32 v3, v1, v1
	v_mul_f32_e32 v9, v7, v7
	s_nop 0
	v_mov_b32_dpp v3, v3 quad_perm:[1,0,3,2] row_mask:0xf bank_mask:0xf bound_ctrl:1
	v_mov_b32_dpp v9, v9 quad_perm:[1,0,3,2] row_mask:0xf bank_mask:0xf bound_ctrl:1
	v_fmac_f32_e32 v3, v1, v1
	v_fmac_f32_e32 v9, v7, v7
	s_nop 0
	v_add_f32_dpp v3, v3, v3 quad_perm:[2,3,0,1] row_mask:0xf bank_mask:0xf bound_ctrl:1
	v_add_f32_dpp v9, v9, v9 quad_perm:[2,3,0,1] row_mask:0xf bank_mask:0xf bound_ctrl:1
	s_nop 0
	v_add_f32_dpp v3, v3, v3 row_half_mirror row_mask:0xf bank_mask:0xf bound_ctrl:1
	v_add_f32_dpp v9, v9, v9 row_half_mirror row_mask:0xf bank_mask:0xf bound_ctrl:1
	s_nop 0
	v_add_f32_dpp v3, v3, v3 row_mirror row_mask:0xf bank_mask:0xf bound_ctrl:1
	v_add_f32_dpp v9, v9, v9 row_mirror row_mask:0xf bank_mask:0xf bound_ctrl:1
	v_mov_b32_e32 v5, v3
	v_mov_b32_e32 v11, v9
	s_nop 0
	v_permlane16_swap_b32_e32 v3, v5
	v_permlane16_swap_b32_e32 v9, v11
	v_add_f32_e32 v47, v3, v5
	v_add_f32_e32 v46, v9, v11
	v_mov_b32_e32 v53, v47
	v_mov_b32_e32 v52, v46
	s_nop 0
	v_permlane32_swap_b32_e32 v47, v53
	v_permlane32_swap_b32_e32 v46, v52
	v_pk_add_f32 v[46:47], v[46:47], v[52:53]
	v_lshlrev_b32_e32 v3, 16, v84
	v_pk_fma_f32 v[44:45], v[46:47], s[2:3], v[44:45] op_sel_hi:[1,0,0]
	v_add_f32_e32 v5, v87, v86
	v_mul_f32_e32 v9, 0x4b800000, v45
	v_cmp_gt_f32_e32 vcc, s0, v45
	v_fma_f32 v5, v5, 0.5, -v3
	v_fmac_f32_e32 v3, v5, v103
	v_cndmask_b32_e32 v9, v45, v9, vcc
	v_rsq_f32_e32 v9, v9
	v_lshlrev_b32_e32 v5, 16, v76
	v_mul_f32_e32 v11, 0x45800000, v9
	v_cndmask_b32_e32 v9, v9, v11, vcc
	v_mul_f32_e32 v1, v1, v9
	s_waitcnt vmcnt(7)
	v_fmac_f32_e32 v112, v106, v1
	v_fmac_f32_e32 v112, v48, v3
	v_mul_f32_e32 v3, 0x4b800000, v44
	v_cmp_gt_f32_e32 vcc, s0, v44
	v_mul_f32_e32 v1, v112, v5
	v_bfe_u32 v5, v1, 16, 1
	v_cndmask_b32_e32 v3, v44, v3, vcc
	v_rsq_f32_e32 v3, v3
	v_add3_u32 v1, v1, v5, s19
	global_store_short_d16_hi v[42:43], v1, off offset:3648
	v_mul_f32_e32 v1, 0x45800000, v3
	v_cndmask_b32_e32 v1, v3, v1, vcc
	v_mul_f32_e32 v1, v7, v1
	s_waitcnt vmcnt(7)
	v_fmac_f32_e32 v113, v107, v1
	v_lshlrev_b32_e32 v1, 16, v88
	v_add_f32_e32 v3, v92, v91
	v_fma_f32 v3, v3, 0.5, -v1
	v_fmac_f32_e32 v1, v3, v104
	v_fmac_f32_e32 v113, v50, v1
	v_lshlrev_b32_e32 v1, 16, v85
	v_mul_f32_e32 v1, v113, v1
	v_bfe_u32 v3, v1, 16, 1
	v_add3_u32 v1, v1, v3, s19
	global_store_short_d16_hi v[42:43], v1, off offset:3776

.LBB0_749:
	s_mov_b32 s0, 0x38e38e39
	v_mul_hi_i32 v1, v2, s0
	v_lshrrev_b32_e32 v3, 31, v1
	v_ashrrev_i32_e32 v1, 9, v1
	v_add_u32_e32 v1, v1, v3
	v_mul_i32_i24_e32 v1, 0x900, v1
	v_sub_u32_e32 v5, v2, v1
	v_readlane_b32 s0, v252, 55
	v_cmp_gt_i32_e64 s[42:43], s8, v5
	v_readlane_b32 s1, v252, 56
	s_and_b64 s[0:1], s[0:1], s[42:43]
	s_xor_b64 s[0:1], s[0:1], -1
	s_and_saveexec_b64 s[48:49], s[0:1]
	s_cbranch_execz .LBB0_748
	v_ashrrev_i32_e32 v3, 31, v2
	v_lshlrev_b64 v[48:49], 9, v[2:3]
	v_or_b32_e32 v42, v48, v4
	v_mov_b32_e32 v43, v49
	v_readlane_b32 s10, v254, 12
	v_readlane_b32 s12, v254, 14
	v_readlane_b32 s2, v254, 10
	v_lshlrev_b64 v[42:43], 1, v[42:43]
	v_readlane_b32 s11, v254, 13
	v_readlane_b32 s13, v254, 15
	v_readlane_b32 s3, v254, 11
	v_lshl_add_u64 v[44:45], s[10:11], 0, v[42:43]
	v_lshl_add_u64 v[46:47], s[12:13], 0, v[42:43]
	v_lshl_add_u64 v[50:51], s[2:3], 0, v[42:43]
	v_mad_i64_i32 v[42:43], s[0:1], v2, s17, v[40:41]
	v_add_co_u32_e32 v52, vcc, 0x1000, v42
	v_cndmask_b32_e64 v7, v239, 0, s[42:43]
	s_nop 0
	v_addc_co_u32_e32 v53, vcc, 0, v43, vcc
	global_load_ushort v97, v[44:45], off
	global_load_ushort v93, v[46:47], off
	global_load_ushort v1, v[50:51], off
	global_load_ushort v94, v[52:53], off offset:832
	v_cmp_gt_i32_e64 s[40:41], v5, v7
	v_mov_b32_e32 v95, 0
	v_mov_b32_e32 v96, 0
	s_and_saveexec_b64 s[6:7], s[40:41]
	s_cbranch_execz .LBB0_752
	v_add_co_u32_e32 v44, vcc, 0xfffff000, v42
	s_nop 1
	v_addc_co_u32_e32 v45, vcc, -1, v43, vcc
	global_load_ushort v96, v[44:45], off offset:-960
.LBB0_752:
	s_or_b64 exec, exec, s[6:7]
	v_cndmask_b32_e64 v7, v241, v240, s[42:43]
	v_cmp_lt_i32_e64 s[42:43], v5, v7
	s_and_saveexec_b64 s[6:7], s[42:43]
	s_cbranch_execz .LBB0_754
	v_add_co_u32_e32 v44, vcc, 0x3000, v42
	s_nop 1
	v_addc_co_u32_e32 v45, vcc, 0, v43, vcc
	global_load_ushort v95, v[44:45], off offset:2624
.LBB0_754:
	s_or_b64 exec, exec, s[6:7]
	v_or_b32_e32 v50, v48, v6
	v_mov_b32_e32 v51, v49
	v_readlane_b32 s0, v252, 5
	v_lshlrev_b64 v[50:51], 1, v[50:51]
	v_lshlrev_b64 v[44:45], 6, v[2:3]
	v_readlane_b32 s1, v252, 6
	v_lshl_add_u64 v[52:53], s[10:11], 0, v[50:51]
	global_load_ushort v98, v[52:53], off
	v_lshl_add_u64 v[46:47], s[0:1], 0, v[44:45]
	v_lshl_add_u64 v[52:53], s[12:13], 0, v[50:51]
	v_lshl_add_u64 v[50:51], s[2:3], 0, v[50:51]
	global_load_dwordx2 v[44:45], v[46:47], off
	global_load_ushort v99, v[52:53], off
	global_load_ushort v3, v[50:51], off
	v_add_co_u32_e32 v52, vcc, 0x1000, v42
	v_lshl_add_u64 v[50:51], v[42:43], 0, s[24:25]
	s_nop 0
	v_addc_co_u32_e32 v53, vcc, 0, v43, vcc
	global_load_ushort v5, v[52:53], off offset:960
	v_mov_b32_e32 v9, 0
	v_mov_b32_e32 v11, 0
	s_and_saveexec_b64 s[6:7], s[40:41]
	s_cbranch_execz .LBB0_756
	v_add_co_u32_e32 v52, vcc, 0xfffff000, v50
	s_nop 1
	v_addc_co_u32_e32 v53, vcc, -1, v51, vcc
	global_load_ushort v11, v[52:53], off offset:-960
.LBB0_756:
	s_or_b64 exec, exec, s[6:7]
	s_and_saveexec_b64 s[6:7], s[42:43]
	s_cbranch_execz .LBB0_758
	v_add_co_u32_e32 v50, vcc, 0x3000, v50
	s_nop 1
	v_addc_co_u32_e32 v51, vcc, 0, v51, vcc
	global_load_ushort v9, v[50:51], off offset:2624
.LBB0_758:
	s_or_b64 exec, exec, s[6:7]
	v_or_b32_e32 v52, v48, v8
	v_mov_b32_e32 v53, v49
	v_lshlrev_b64 v[52:53], 1, v[52:53]
	v_lshl_add_u64 v[54:55], s[10:11], 0, v[52:53]
	global_load_ushort v13, v[54:55], off
	v_lshl_add_u64 v[54:55], s[12:13], 0, v[52:53]
	v_lshl_add_u64 v[52:53], s[2:3], 0, v[52:53]
	global_load_dwordx2 v[50:51], v[46:47], off offset:8
	global_load_ushort v15, v[54:55], off
	global_load_ushort v7, v[52:53], off
	v_add_co_u32_e32 v54, vcc, 0x1000, v42
	s_mov_b64 s[0:1], 0x100
	s_nop 0
	v_addc_co_u32_e32 v55, vcc, 0, v43, vcc
	global_load_ushort v17, v[54:55], off offset:1088
	v_lshl_add_u64 v[52:53], v[42:43], 0, s[0:1]
	v_mov_b32_e32 v62, 0
	v_mov_b32_e32 v63, 0
	s_and_saveexec_b64 s[6:7], s[40:41]
	s_cbranch_execz .LBB0_760
	v_add_co_u32_e32 v54, vcc, 0xfffff000, v52
	s_nop 1
	v_addc_co_u32_e32 v55, vcc, -1, v53, vcc
	global_load_ushort v63, v[54:55], off offset:-960
.LBB0_760:
	s_or_b64 exec, exec, s[6:7]
	s_and_saveexec_b64 s[6:7], s[42:43]
	s_cbranch_execz .LBB0_762
	v_add_co_u32_e32 v52, vcc, 0x3000, v52
	s_nop 1
	v_addc_co_u32_e32 v53, vcc, 0, v53, vcc
	global_load_ushort v62, v[52:53], off offset:2624
.LBB0_762:
	s_or_b64 exec, exec, s[6:7]
	v_or_b32_e32 v54, v48, v10
	v_mov_b32_e32 v55, v49
	v_lshlrev_b64 v[54:55], 1, v[54:55]
	v_lshl_add_u64 v[56:57], s[10:11], 0, v[54:55]
	global_load_ushort v66, v[56:57], off
	v_lshl_add_u64 v[56:57], s[12:13], 0, v[54:55]
	v_lshl_add_u64 v[54:55], s[2:3], 0, v[54:55]
	global_load_dwordx2 v[52:53], v[46:47], off offset:16
	global_load_ushort v67, v[56:57], off
	global_load_ushort v19, v[54:55], off
	v_add_co_u32_e32 v56, vcc, 0x1000, v42
	s_mov_b64 s[0:1], 0x180
	s_nop 0
	v_addc_co_u32_e32 v57, vcc, 0, v43, vcc
	global_load_ushort v64, v[56:57], off offset:1216
	v_lshl_add_u64 v[54:55], v[42:43], 0, s[0:1]
	v_mov_b32_e32 v68, 0
	v_mov_b32_e32 v69, 0
	s_and_saveexec_b64 s[6:7], s[40:41]
	s_cbranch_execz .LBB0_764
	v_add_co_u32_e32 v56, vcc, 0xfffff000, v54
	s_nop 1
	v_addc_co_u32_e32 v57, vcc, -1, v55, vcc
	global_load_ushort v69, v[56:57], off offset:-960
.LBB0_764:
	s_or_b64 exec, exec, s[6:7]
	s_and_saveexec_b64 s[6:7], s[42:43]
	s_cbranch_execz .LBB0_766
	v_add_co_u32_e32 v54, vcc, 0x3000, v54
	s_nop 1
	v_addc_co_u32_e32 v55, vcc, 0, v55, vcc
	global_load_ushort v68, v[54:55], off offset:2624
.LBB0_766:
	s_or_b64 exec, exec, s[6:7]
	v_or_b32_e32 v56, v48, v12
	v_mov_b32_e32 v57, v49
	v_lshlrev_b64 v[56:57], 1, v[56:57]
	v_lshl_add_u64 v[58:59], s[10:11], 0, v[56:57]
	global_load_ushort v70, v[58:59], off
	v_lshl_add_u64 v[58:59], s[12:13], 0, v[56:57]
	v_lshl_add_u64 v[56:57], s[2:3], 0, v[56:57]
	global_load_dwordx2 v[54:55], v[46:47], off offset:24
	global_load_ushort v71, v[58:59], off
	global_load_ushort v65, v[56:57], off
	v_add_co_u32_e32 v58, vcc, 0x1000, v42
	s_mov_b64 s[0:1], 0x200
	s_nop 0
	v_addc_co_u32_e32 v59, vcc, 0, v43, vcc
	global_load_ushort v72, v[58:59], off offset:1344
	v_lshl_add_u64 v[56:57], v[42:43], 0, s[0:1]
	v_mov_b32_e32 v74, 0
	v_mov_b32_e32 v75, 0
	s_and_saveexec_b64 s[6:7], s[40:41]
	s_cbranch_execz .LBB0_768
	v_add_co_u32_e32 v58, vcc, 0xfffff000, v56
	s_nop 1
	v_addc_co_u32_e32 v59, vcc, -1, v57, vcc
	global_load_ushort v75, v[58:59], off offset:-960
.LBB0_768:
	s_or_b64 exec, exec, s[6:7]
	s_and_saveexec_b64 s[6:7], s[42:43]
	s_cbranch_execz .LBB0_770
	v_add_co_u32_e32 v56, vcc, 0x3000, v56
	s_nop 1
	v_addc_co_u32_e32 v57, vcc, 0, v57, vcc
	global_load_ushort v74, v[56:57], off offset:2624
.LBB0_770:
	s_or_b64 exec, exec, s[6:7]
	v_or_b32_e32 v58, v48, v14
	v_mov_b32_e32 v59, v49
	v_lshlrev_b64 v[58:59], 1, v[58:59]
	v_lshl_add_u64 v[60:61], s[10:11], 0, v[58:59]
	global_load_ushort v78, v[60:61], off
	v_lshl_add_u64 v[60:61], s[12:13], 0, v[58:59]
	v_lshl_add_u64 v[58:59], s[2:3], 0, v[58:59]
	global_load_dwordx2 v[56:57], v[46:47], off offset:32
	global_load_ushort v79, v[60:61], off
	global_load_ushort v73, v[58:59], off
	v_add_co_u32_e32 v60, vcc, 0x1000, v42
	s_mov_b64 s[0:1], 0x280
	s_nop 0
	v_addc_co_u32_e32 v61, vcc, 0, v43, vcc
	global_load_ushort v77, v[60:61], off offset:1472
	v_lshl_add_u64 v[58:59], v[42:43], 0, s[0:1]
	v_mov_b32_e32 v80, 0
	v_mov_b32_e32 v81, 0
	s_and_saveexec_b64 s[6:7], s[40:41]
	s_cbranch_execz .LBB0_772
	v_add_co_u32_e32 v60, vcc, 0xfffff000, v58
	s_nop 1
	v_addc_co_u32_e32 v61, vcc, -1, v59, vcc
	global_load_ushort v81, v[60:61], off offset:-960
.LBB0_772:
	s_or_b64 exec, exec, s[6:7]
	s_and_saveexec_b64 s[6:7], s[42:43]
	s_cbranch_execz .LBB0_774
	v_add_co_u32_e32 v58, vcc, 0x3000, v58
	s_nop 1
	v_addc_co_u32_e32 v59, vcc, 0, v59, vcc
	global_load_ushort v80, v[58:59], off offset:2624
.LBB0_774:
	s_or_b64 exec, exec, s[6:7]
	v_or_b32_e32 v60, v48, v16
	v_mov_b32_e32 v61, v49
	v_lshlrev_b64 v[60:61], 1, v[60:61]
	v_lshl_add_u64 v[82:83], s[10:11], 0, v[60:61]
	v_lshl_add_u64 v[84:85], s[12:13], 0, v[60:61]
	v_lshl_add_u64 v[60:61], s[2:3], 0, v[60:61]
	global_load_dwordx2 v[58:59], v[46:47], off offset:40
	global_load_ushort v76, v[60:61], off
	s_mov_b64 s[0:1], 0x300
	global_load_ushort v82, v[82:83], off
	v_lshl_add_u64 v[60:61], v[42:43], 0, s[0:1]
	global_load_ushort v83, v[84:85], off
	v_add_co_u32_e32 v84, vcc, 0x1000, v42
	v_mov_b32_e32 v86, 0
	s_nop 0
	v_addc_co_u32_e32 v85, vcc, 0, v43, vcc
	global_load_ushort v84, v[84:85], off offset:1600
	v_mov_b32_e32 v87, 0
	s_and_saveexec_b64 s[6:7], s[40:41]
	s_cbranch_execz .LBB0_776
	v_add_co_u32_e32 v88, vcc, 0xfffff000, v60
	s_nop 1
	v_addc_co_u32_e32 v89, vcc, -1, v61, vcc
	global_load_ushort v87, v[88:89], off offset:-960
.LBB0_776:
	s_or_b64 exec, exec, s[6:7]
	s_and_saveexec_b64 s[6:7], s[42:43]
	s_cbranch_execz .LBB0_778
	v_add_co_u32_e32 v60, vcc, 0x3000, v60
	s_nop 1
	v_addc_co_u32_e32 v61, vcc, 0, v61, vcc
	global_load_ushort v86, v[60:61], off offset:2624

.LBB0_780:
	s_or_b64 exec, exec, s[6:7]
	s_and_saveexec_b64 s[6:7], s[42:43]
	s_cbranch_execz .LBB0_747
	v_add_co_u32_e32 v48, vcc, 0x3000, v48
	s_nop 1
	v_addc_co_u32_e32 v49, vcc, 0, v49, vcc
	global_load_ushort v91, v[48:49], off offset:2624
	s_branch .LBB0_747

.LBB0_931:
	s_or_b64 exec, exec, s[6:7]
	v_ashrrev_i32_e32 v19, 31, v18
	v_lshlrev_b64 v[18:19], 12, v[18:19]
	v_ashrrev_i32_e32 v25, 31, v24
	v_lshl_add_u64 v[18:19], v[22:23], 0, v[18:19]
	v_lshlrev_b64 v[22:23], 12, v[24:25]
	v_lshl_add_u64 v[22:23], v[26:27], 0, v[22:23]
	v_lshl_add_u64 v[28:29], v[68:69], 0, v[20:21]
	v_lshl_add_u64 v[26:27], v[18:19], 0, v[66:67]
	v_lshl_add_u64 v[30:31], v[22:23], 0, v[66:67]
	global_load_dwordx4 v[202:205], v[28:29], off
	global_load_dwordx4 v[206:209], v[30:31], off
	global_load_dwordx4 v[210:213], v[28:29], off offset:64
	global_load_dwordx4 v[214:217], v[30:31], off offset:64
	global_load_dwordx4 v[218:221], v[28:29], off offset:128
	global_load_dwordx4 v[222:225], v[30:31], off offset:128
	global_load_dwordx4 v[226:229], v[28:29], off offset:192
	global_load_dwordx4 v[230:233], v[30:31], off offset:192
	s_waitcnt vmcnt(0)
	v_pk_fma_f32 v[14:15], v[14:15], v[202:203], v[206:207]
	v_pk_fma_f32 v[16:17], v[16:17], v[204:205], v[208:209]
	v_pk_fma_f32 v[10:11], v[10:11], v[210:211], v[214:215]
	v_pk_fma_f32 v[12:13], v[12:13], v[212:213], v[216:217]
	v_pk_fma_f32 v[6:7], v[6:7], v[218:219], v[222:223]
	v_pk_fma_f32 v[8:9], v[8:9], v[220:221], v[224:225]
	v_pk_fma_f32 v[2:3], v[2:3], v[226:227], v[230:231]
	v_pk_fma_f32 v[4:5], v[4:5], v[228:229], v[232:233]
	global_store_dwordx4 v[26:27], v[14:17], off
	global_store_dwordx4 v[26:27], v[10:13], off offset:64
	global_store_dwordx4 v[26:27], v[6:9], off offset:128
	global_store_dwordx4 v[26:27], v[2:5], off offset:192

.LBB0_954:
	s_andn2_saveexec_b64 s[12:13], s[12:13]
	v_lshl_add_u32 v72, v73, 8, v67
	v_mov_b64_e32 v[70:71], 0x60000
	s_or_b64 exec, exec, s[12:13]
	v_ashrrev_i32_e32 v67, 31, v66
	v_lshlrev_b64 v[66:67], 12, v[66:67]
	v_lshl_add_u64 v[78:79], v[68:69], 0, v[66:67]
	v_or_b32_e32 v66, s6, v114
	v_ashrrev_i32_e32 v67, 31, v66
	v_lshlrev_b64 v[66:67], 2, v[66:67]
	v_ashrrev_i32_e32 v73, 31, v72
	v_lshl_add_u64 v[68:69], s[40:41], 0, v[66:67]
	v_lshlrev_b64 v[72:73], 12, v[72:73]
	v_lshl_add_u64 v[72:73], v[74:75], 0, v[72:73]
	v_lshl_add_u64 v[82:83], v[68:69], 0, v[70:71]
	v_lshl_add_u64 v[74:75], v[78:79], 0, v[66:67]
	v_lshl_add_u64 v[84:85], v[72:73], 0, v[66:67]
	global_load_dwordx4 v[202:205], v[82:83], off
	global_load_dwordx4 v[206:209], v[84:85], off
	global_load_dwordx4 v[210:213], v[82:83], off offset:64
	global_load_dwordx4 v[214:217], v[84:85], off offset:64
	global_load_dwordx4 v[218:221], v[82:83], off offset:128
	global_load_dwordx4 v[222:225], v[84:85], off offset:128
	global_load_dwordx4 v[226:229], v[82:83], off offset:192
	global_load_dwordx4 v[230:233], v[84:85], off offset:192
	s_mov_b32 s2, 0x38e38e39
	s_waitcnt vmcnt(0)
	v_pk_fma_f32 v[62:63], v[62:63], v[202:203], v[206:207]
	v_pk_fma_f32 v[64:65], v[64:65], v[204:205], v[208:209]
	v_pk_fma_f32 v[58:59], v[58:59], v[210:211], v[214:215]
	v_pk_fma_f32 v[60:61], v[60:61], v[212:213], v[216:217]
	v_pk_fma_f32 v[54:55], v[54:55], v[218:219], v[222:223]
	v_pk_fma_f32 v[56:57], v[56:57], v[220:221], v[224:225]
	v_pk_fma_f32 v[50:51], v[50:51], v[226:227], v[230:231]
	v_pk_fma_f32 v[52:53], v[52:53], v[228:229], v[232:233]
	global_store_dwordx4 v[74:75], v[62:65], off
	global_store_dwordx4 v[74:75], v[58:61], off offset:64
	global_store_dwordx4 v[74:75], v[54:57], off offset:128
	global_store_dwordx4 v[74:75], v[50:53], off offset:192
	s_nop 1
	v_or_b32_e32 v50, 16, v76
	v_mul_hi_i32 v51, v50, s2
	v_lshrrev_b32_e32 v52, 31, v51
	v_ashrrev_i32_e32 v51, 9, v51
	v_add_u32_e32 v52, v51, v52
	v_mad_i32_i24 v51, v52, s53, v50
	v_cmp_lt_i32_e32 vcc, s39, v51
	s_and_saveexec_b64 s[2:3], vcc
	s_xor_b64 s[6:7], exec, s[2:3]
	s_cbranch_execz .LBB0_958
	v_lshlrev_b32_e32 v50, 11, v52
	v_readlane_b32 s2, v252, 54
	s_nop 1
	v_add3_u32 v50, v50, s2, v51

.LBB0_962:
	s_andn2_saveexec_b64 s[6:7], s[6:7]
	v_lshl_add_u32 v56, v57, 8, v51
	v_mov_b64_e32 v[52:53], 0x60000
	s_or_b64 exec, exec, s[6:7]
	v_ashrrev_i32_e32 v51, 31, v50
	v_lshlrev_b64 v[50:51], 12, v[50:51]
	v_ashrrev_i32_e32 v57, 31, v56
	v_lshl_add_u64 v[50:51], v[54:55], 0, v[50:51]
	v_lshlrev_b64 v[54:55], 12, v[56:57]
	v_lshl_add_u64 v[54:55], v[58:59], 0, v[54:55]
	v_lshl_add_u64 v[60:61], v[68:69], 0, v[52:53]
	v_lshl_add_u64 v[58:59], v[50:51], 0, v[66:67]
	v_lshl_add_u64 v[62:63], v[54:55], 0, v[66:67]
	global_load_dwordx4 v[202:205], v[60:61], off
	global_load_dwordx4 v[206:209], v[62:63], off
	global_load_dwordx4 v[210:213], v[60:61], off offset:64
	global_load_dwordx4 v[214:217], v[62:63], off offset:64
	global_load_dwordx4 v[218:221], v[60:61], off offset:128
	global_load_dwordx4 v[222:225], v[62:63], off offset:128
	global_load_dwordx4 v[226:229], v[60:61], off offset:192
	global_load_dwordx4 v[230:233], v[62:63], off offset:192
	s_mov_b32 s2, 0x38e38e39
	s_waitcnt vmcnt(0)
	v_pk_fma_f32 v[46:47], v[46:47], v[202:203], v[206:207]
	v_pk_fma_f32 v[48:49], v[48:49], v[204:205], v[208:209]
	v_pk_fma_f32 v[42:43], v[42:43], v[210:211], v[214:215]
	v_pk_fma_f32 v[44:45], v[44:45], v[212:213], v[216:217]
	v_pk_fma_f32 v[38:39], v[38:39], v[218:219], v[222:223]
	v_pk_fma_f32 v[40:41], v[40:41], v[220:221], v[224:225]
	v_pk_fma_f32 v[34:35], v[34:35], v[226:227], v[230:231]
	v_pk_fma_f32 v[36:37], v[36:37], v[228:229], v[232:233]
	global_store_dwordx4 v[58:59], v[46:49], off
	global_store_dwordx4 v[58:59], v[42:45], off offset:64
	global_store_dwordx4 v[58:59], v[38:41], off offset:128
	global_store_dwordx4 v[58:59], v[34:37], off offset:192
	s_nop 1
	v_or_b32_e32 v34, 32, v76
	v_mul_hi_i32 v35, v34, s2
	v_lshrrev_b32_e32 v36, 31, v35
	v_ashrrev_i32_e32 v35, 9, v35
	v_add_u32_e32 v36, v35, v36
	v_mad_i32_i24 v35, v36, s53, v34
	v_cmp_lt_i32_e32 vcc, s39, v35
	s_and_saveexec_b64 s[2:3], vcc
	s_xor_b64 s[6:7], exec, s[2:3]
	s_cbranch_execz .LBB0_966
	v_lshlrev_b32_e32 v34, 11, v36
	v_readlane_b32 s2, v252, 54
	s_nop 1
	v_add3_u32 v34, v34, s2, v35

.LBB0_970:
	s_andn2_saveexec_b64 s[6:7], s[6:7]
	v_lshl_add_u32 v40, v41, 8, v35
	v_mov_b64_e32 v[36:37], 0x60000
	s_or_b64 exec, exec, s[6:7]
	v_ashrrev_i32_e32 v35, 31, v34
	v_lshlrev_b64 v[34:35], 12, v[34:35]
	v_ashrrev_i32_e32 v41, 31, v40
	v_lshl_add_u64 v[34:35], v[38:39], 0, v[34:35]
	v_lshlrev_b64 v[38:39], 12, v[40:41]
	v_lshl_add_u64 v[38:39], v[42:43], 0, v[38:39]
	v_lshl_add_u64 v[44:45], v[68:69], 0, v[36:37]
	v_lshl_add_u64 v[42:43], v[34:35], 0, v[66:67]
	v_lshl_add_u64 v[46:47], v[38:39], 0, v[66:67]
	global_load_dwordx4 v[202:205], v[44:45], off
	global_load_dwordx4 v[206:209], v[46:47], off
	global_load_dwordx4 v[210:213], v[44:45], off offset:64
	global_load_dwordx4 v[214:217], v[46:47], off offset:64
	global_load_dwordx4 v[218:221], v[44:45], off offset:128
	global_load_dwordx4 v[222:225], v[46:47], off offset:128
	global_load_dwordx4 v[226:229], v[44:45], off offset:192
	global_load_dwordx4 v[230:233], v[46:47], off offset:192
	s_mov_b32 s2, 0x38e38e39
	s_waitcnt vmcnt(0)
	v_pk_fma_f32 v[30:31], v[30:31], v[202:203], v[206:207]
	v_pk_fma_f32 v[32:33], v[32:33], v[204:205], v[208:209]
	v_pk_fma_f32 v[26:27], v[26:27], v[210:211], v[214:215]
	v_pk_fma_f32 v[28:29], v[28:29], v[212:213], v[216:217]
	v_pk_fma_f32 v[22:23], v[22:23], v[218:219], v[222:223]
	v_pk_fma_f32 v[24:25], v[24:25], v[220:221], v[224:225]
	v_pk_fma_f32 v[18:19], v[18:19], v[226:227], v[230:231]
	v_pk_fma_f32 v[20:21], v[20:21], v[228:229], v[232:233]
	global_store_dwordx4 v[42:43], v[30:33], off
	global_store_dwordx4 v[42:43], v[26:29], off offset:64
	global_store_dwordx4 v[42:43], v[22:25], off offset:128
	global_store_dwordx4 v[42:43], v[18:21], off offset:192
	s_nop 1
	v_or_b32_e32 v18, 48, v76
	v_mul_hi_i32 v19, v18, s2
	v_lshrrev_b32_e32 v20, 31, v19
	v_ashrrev_i32_e32 v19, 9, v19
	v_add_u32_e32 v20, v19, v20
	v_mad_i32_i24 v19, v20, s53, v18
	v_cmp_lt_i32_e32 vcc, s39, v19
	s_and_saveexec_b64 s[2:3], vcc
	s_xor_b64 s[6:7], exec, s[2:3]
	s_cbranch_execz .LBB0_974
	v_lshlrev_b32_e32 v18, 11, v20
	v_readlane_b32 s2, v252, 54
	s_nop 1
	v_add3_u32 v18, v18, s2, v19

.LBB0_984:
	s_or_b64 exec, exec, s[6:7]
	v_ashrrev_i32_e32 v19, 31, v18
	v_lshlrev_b64 v[18:19], 12, v[18:19]
	v_lshl_add_u64 v[18:19], v[22:23], 0, v[18:19]
	v_lshl_add_u64 v[28:29], v[140:141], 0, v[20:21]
	v_lshl_add_u64 v[26:27], v[138:139], 2, v[18:19]
	global_load_dwordx4 v[202:205], v[28:29], off
	global_load_dwordx4 v[206:209], v[26:27], off
	global_load_dwordx4 v[210:213], v[28:29], off offset:64
	global_load_dwordx4 v[214:217], v[26:27], off offset:64
	global_load_dwordx4 v[218:221], v[28:29], off offset:128
	global_load_dwordx4 v[222:225], v[26:27], off offset:128
	global_load_dwordx4 v[226:229], v[28:29], off offset:192
	global_load_dwordx4 v[230:233], v[26:27], off offset:192
	s_waitcnt vmcnt(0)
	v_pk_fma_f32 v[14:15], v[14:15], v[202:203], v[206:207]
	v_pk_fma_f32 v[16:17], v[16:17], v[204:205], v[208:209]
	v_pk_fma_f32 v[10:11], v[10:11], v[210:211], v[214:215]
	v_pk_fma_f32 v[12:13], v[12:13], v[212:213], v[216:217]
	v_pk_fma_f32 v[6:7], v[6:7], v[218:219], v[222:223]
	v_pk_fma_f32 v[8:9], v[8:9], v[220:221], v[224:225]
	v_pk_fma_f32 v[2:3], v[2:3], v[226:227], v[230:231]
	v_pk_fma_f32 v[4:5], v[4:5], v[228:229], v[232:233]
	global_store_dwordx4 v[26:27], v[14:17], off
	global_store_dwordx4 v[26:27], v[10:13], off offset:64
	global_store_dwordx4 v[26:27], v[6:9], off offset:128
	global_store_dwordx4 v[26:27], v[2:5], off offset:192

.LBB0_993:
	s_or_saveexec_b64 s[6:7], s[6:7]
	v_readlane_b32 s12, v252, 28
	v_readlane_b32 s14, v252, 30
	v_readlane_b32 s15, v252, 31
	v_readlane_b32 s13, v252, 29
	s_nop 0
	v_mov_b64_e32 v[146:147], s[14:15]
	s_xor_b64 exec, exec, s[6:7]
	v_lshl_add_u32 v142, v138, 8, v139
	v_mov_b64_e32 v[144:145], 0x60000
	v_mov_b64_e32 v[146:147], s[68:69]
	s_or_b64 exec, exec, s[6:7]
	v_or_b32_e32 v138, s26, v152
	v_ashrrev_i32_e32 v139, 31, v138
	v_lshlrev_b64 v[156:157], 2, v[138:139]
	v_ashrrev_i32_e32 v143, 31, v142
	v_lshl_add_u64 v[140:141], s[42:43], 0, v[156:157]
	v_lshlrev_b64 v[142:143], 12, v[142:143]
	v_lshl_add_u64 v[142:143], v[146:147], 0, v[142:143]
	v_lshl_add_u64 v[160:161], v[140:141], 0, v[144:145]
	v_lshl_add_u64 v[146:147], v[142:143], 0, v[156:157]
	global_load_dwordx4 v[202:205], v[160:161], off
	global_load_dwordx4 v[206:209], v[146:147], off
	global_load_dwordx4 v[210:213], v[160:161], off offset:64
	global_load_dwordx4 v[214:217], v[146:147], off offset:64
	global_load_dwordx4 v[218:221], v[160:161], off offset:128
	global_load_dwordx4 v[222:225], v[146:147], off offset:128
	global_load_dwordx4 v[226:229], v[160:161], off offset:192
	global_load_dwordx4 v[230:233], v[146:147], off offset:192
	s_mov_b32 s2, 0x38e38e39
	s_waitcnt vmcnt(0)
	v_pk_fma_f32 v[126:127], v[126:127], v[202:203], v[206:207]
	v_pk_fma_f32 v[128:129], v[128:129], v[204:205], v[208:209]
	v_pk_fma_f32 v[122:123], v[122:123], v[210:211], v[214:215]
	v_pk_fma_f32 v[124:125], v[124:125], v[212:213], v[216:217]
	v_pk_fma_f32 v[118:119], v[118:119], v[218:219], v[222:223]
	v_pk_fma_f32 v[120:121], v[120:121], v[220:221], v[224:225]
	v_pk_fma_f32 v[114:115], v[114:115], v[226:227], v[230:231]
	v_pk_fma_f32 v[116:117], v[116:117], v[228:229], v[232:233]
	global_store_dwordx4 v[146:147], v[126:129], off
	global_store_dwordx4 v[146:147], v[122:125], off offset:64
	global_store_dwordx4 v[146:147], v[118:121], off offset:128
	global_store_dwordx4 v[146:147], v[114:117], off offset:192
	s_nop 1
	v_or_b32_e32 v114, 16, v155
	v_mul_hi_i32 v115, v114, s2
	v_lshrrev_b32_e32 v116, 31, v115
	v_ashrrev_i32_e32 v115, 9, v115
	v_add_u32_e32 v115, v115, v116
	v_mad_i32_i24 v120, v115, s53, v114
	v_cmp_lt_i32_e32 vcc, s39, v120
	s_and_saveexec_b64 s[2:3], vcc
	s_xor_b64 s[6:7], exec, s[2:3]
	s_cbranch_execz .LBB0_997
	v_readlane_b32 s2, v252, 34
	v_lshlrev_b32_e32 v114, 11, v115
	s_nop 0
	v_add_u32_e32 v116, s2, v115
	v_readlane_b32 s2, v252, 54
	v_mul_hi_i32_i24_e32 v117, 0x6000, v116
	v_mul_i32_i24_e32 v116, 0x6000, v116
	v_add3_u32 v114, v114, s2, v120
.LBB0_997:
	s_or_saveexec_b64 s[6:7], s[6:7]
	v_readlane_b32 s12, v252, 28
	v_readlane_b32 s14, v252, 30
	v_readlane_b32 s15, v252, 31
	v_readlane_b32 s13, v252, 29
	s_nop 0
	v_mov_b64_e32 v[118:119], s[14:15]
	s_xor_b64 exec, exec, s[6:7]
	v_lshl_add_u32 v114, v115, 8, v120
	v_mov_b64_e32 v[116:117], 0x60000
	v_mov_b64_e32 v[118:119], s[68:69]
	s_or_b64 exec, exec, s[6:7]
	v_ashrrev_i32_e32 v115, 31, v114
	v_lshlrev_b64 v[114:115], 12, v[114:115]
	v_lshl_add_u64 v[114:115], v[118:119], 0, v[114:115]
	v_lshl_add_u64 v[124:125], v[140:141], 0, v[116:117]
	v_lshl_add_u64 v[122:123], v[138:139], 2, v[114:115]
	global_load_dwordx4 v[202:205], v[124:125], off
	global_load_dwordx4 v[206:209], v[122:123], off
	global_load_dwordx4 v[210:213], v[124:125], off offset:64
	global_load_dwordx4 v[214:217], v[122:123], off offset:64
	global_load_dwordx4 v[218:221], v[124:125], off offset:128
	global_load_dwordx4 v[222:225], v[122:123], off offset:128
	global_load_dwordx4 v[226:229], v[124:125], off offset:192
	global_load_dwordx4 v[230:233], v[122:123], off offset:192
	s_mov_b32 s2, 0x38e38e39
	s_waitcnt vmcnt(0)
	v_pk_fma_f32 v[110:111], v[110:111], v[202:203], v[206:207]
	v_pk_fma_f32 v[112:113], v[112:113], v[204:205], v[208:209]
	v_pk_fma_f32 v[106:107], v[106:107], v[210:211], v[214:215]
	v_pk_fma_f32 v[108:109], v[108:109], v[212:213], v[216:217]
	v_pk_fma_f32 v[102:103], v[102:103], v[218:219], v[222:223]
	v_pk_fma_f32 v[104:105], v[104:105], v[220:221], v[224:225]
	v_pk_fma_f32 v[98:99], v[98:99], v[226:227], v[230:231]
	v_pk_fma_f32 v[100:101], v[100:101], v[228:229], v[232:233]
	global_store_dwordx4 v[122:123], v[110:113], off
	global_store_dwordx4 v[122:123], v[106:109], off offset:64
	global_store_dwordx4 v[122:123], v[102:105], off offset:128
	global_store_dwordx4 v[122:123], v[98:101], off offset:192
	s_nop 1
	v_or_b32_e32 v98, 32, v155
	v_mul_hi_i32 v99, v98, s2
	v_lshrrev_b32_e32 v100, 31, v99
	v_ashrrev_i32_e32 v99, 9, v99
	v_add_u32_e32 v99, v99, v100
	v_mad_i32_i24 v104, v99, s53, v98
	v_cmp_lt_i32_e32 vcc, s39, v104
	s_and_saveexec_b64 s[2:3], vcc
	s_xor_b64 s[6:7], exec, s[2:3]
	s_cbranch_execz .LBB0_1001
	v_readlane_b32 s2, v252, 34
	v_lshlrev_b32_e32 v98, 11, v99
	s_nop 0
	v_add_u32_e32 v100, s2, v99
	v_readlane_b32 s2, v252, 54
	v_mul_hi_i32_i24_e32 v101, 0x6000, v100
	v_mul_i32_i24_e32 v100, 0x6000, v100
	v_add3_u32 v98, v98, s2, v104
.LBB0_1001:
	s_or_saveexec_b64 s[6:7], s[6:7]
	v_readlane_b32 s12, v252, 28
	v_readlane_b32 s14, v252, 30
	v_readlane_b32 s15, v252, 31
	v_readlane_b32 s13, v252, 29
	s_nop 0
	v_mov_b64_e32 v[102:103], s[14:15]
	s_xor_b64 exec, exec, s[6:7]
	v_lshl_add_u32 v98, v99, 8, v104
	v_mov_b64_e32 v[100:101], 0x60000
	v_mov_b64_e32 v[102:103], s[68:69]
	s_or_b64 exec, exec, s[6:7]
	v_ashrrev_i32_e32 v99, 31, v98
	v_lshlrev_b64 v[98:99], 12, v[98:99]
	v_lshl_add_u64 v[98:99], v[102:103], 0, v[98:99]
	v_lshl_add_u64 v[108:109], v[140:141], 0, v[100:101]
	v_lshl_add_u64 v[106:107], v[138:139], 2, v[98:99]
	global_load_dwordx4 v[202:205], v[108:109], off
	global_load_dwordx4 v[206:209], v[106:107], off
	global_load_dwordx4 v[210:213], v[108:109], off offset:64
	global_load_dwordx4 v[214:217], v[106:107], off offset:64
	global_load_dwordx4 v[218:221], v[108:109], off offset:128
	global_load_dwordx4 v[222:225], v[106:107], off offset:128
	global_load_dwordx4 v[226:229], v[108:109], off offset:192
	global_load_dwordx4 v[230:233], v[106:107], off offset:192
	s_mov_b32 s2, 0x38e38e39
	s_waitcnt vmcnt(0)
	v_pk_fma_f32 v[94:95], v[94:95], v[202:203], v[206:207]
	v_pk_fma_f32 v[96:97], v[96:97], v[204:205], v[208:209]
	v_pk_fma_f32 v[90:91], v[90:91], v[210:211], v[214:215]
	v_pk_fma_f32 v[92:93], v[92:93], v[212:213], v[216:217]
	v_pk_fma_f32 v[86:87], v[86:87], v[218:219], v[222:223]
	v_pk_fma_f32 v[88:89], v[88:89], v[220:221], v[224:225]
	v_pk_fma_f32 v[82:83], v[82:83], v[226:227], v[230:231]
	v_pk_fma_f32 v[84:85], v[84:85], v[228:229], v[232:233]
	global_store_dwordx4 v[106:107], v[94:97], off
	global_store_dwordx4 v[106:107], v[90:93], off offset:64
	global_store_dwordx4 v[106:107], v[86:89], off offset:128
	global_store_dwordx4 v[106:107], v[82:85], off offset:192
	s_nop 1
	v_or_b32_e32 v82, 48, v155
	v_mul_hi_i32 v83, v82, s2
	v_lshrrev_b32_e32 v84, 31, v83
	v_ashrrev_i32_e32 v83, 9, v83
	v_add_u32_e32 v83, v83, v84
	v_mad_i32_i24 v88, v83, s53, v82
	v_cmp_lt_i32_e32 vcc, s39, v88
	s_and_saveexec_b64 s[2:3], vcc
	s_xor_b64 s[6:7], exec, s[2:3]
	s_cbranch_execz .LBB0_1005
	v_readlane_b32 s2, v252, 34
	v_lshlrev_b32_e32 v82, 11, v83
	s_nop 0
	v_add_u32_e32 v84, s2, v83
	v_readlane_b32 s2, v252, 54
	v_mul_hi_i32_i24_e32 v85, 0x6000, v84
	v_mul_i32_i24_e32 v84, 0x6000, v84
	v_add3_u32 v82, v82, s2, v88
.LBB0_1005:
	s_or_saveexec_b64 s[6:7], s[6:7]
	v_readlane_b32 s12, v252, 28
	v_readlane_b32 s14, v252, 30
	v_readlane_b32 s15, v252, 31
	v_readlane_b32 s13, v252, 29
	s_nop 0
	v_mov_b64_e32 v[86:87], s[14:15]
	s_xor_b64 exec, exec, s[6:7]
	v_lshl_add_u32 v82, v83, 8, v88
	v_mov_b64_e32 v[84:85], 0x60000
	v_mov_b64_e32 v[86:87], s[68:69]
	s_or_b64 exec, exec, s[6:7]
	v_ashrrev_i32_e32 v83, 31, v82
	v_lshlrev_b64 v[82:83], 12, v[82:83]
	v_lshl_add_u64 v[82:83], v[86:87], 0, v[82:83]
	v_lshl_add_u64 v[92:93], v[140:141], 0, v[84:85]
	v_lshl_add_u64 v[90:91], v[138:139], 2, v[82:83]
	global_load_dwordx4 v[202:205], v[92:93], off
	global_load_dwordx4 v[206:209], v[90:91], off
	global_load_dwordx4 v[210:213], v[92:93], off offset:64
	global_load_dwordx4 v[214:217], v[90:91], off offset:64
	global_load_dwordx4 v[218:221], v[92:93], off offset:128
	global_load_dwordx4 v[222:225], v[90:91], off offset:128
	global_load_dwordx4 v[226:229], v[92:93], off offset:192
	global_load_dwordx4 v[230:233], v[90:91], off offset:192
	s_mov_b32 s2, 0x38e38e39
	s_waitcnt vmcnt(0)
	v_pk_fma_f32 v[78:79], v[78:79], v[202:203], v[206:207]
	v_pk_fma_f32 v[80:81], v[80:81], v[204:205], v[208:209]
	v_pk_fma_f32 v[74:75], v[74:75], v[210:211], v[214:215]
	v_pk_fma_f32 v[76:77], v[76:77], v[212:213], v[216:217]
	v_pk_fma_f32 v[70:71], v[70:71], v[218:219], v[222:223]
	v_pk_fma_f32 v[72:73], v[72:73], v[220:221], v[224:225]
	v_pk_fma_f32 v[66:67], v[66:67], v[226:227], v[230:231]
	v_pk_fma_f32 v[68:69], v[68:69], v[228:229], v[232:233]
	global_store_dwordx4 v[90:91], v[78:81], off
	global_store_dwordx4 v[90:91], v[74:77], off offset:64
	global_store_dwordx4 v[90:91], v[70:73], off offset:128
	global_store_dwordx4 v[90:91], v[66:69], off offset:192
	s_nop 1
	v_or_b32_e32 v66, 64, v155
	v_mul_hi_i32 v67, v66, s2
	v_lshrrev_b32_e32 v68, 31, v67
	v_ashrrev_i32_e32 v67, 9, v67
	v_add_u32_e32 v67, v67, v68
	v_mad_i32_i24 v72, v67, s53, v66
	v_cmp_lt_i32_e32 vcc, s39, v72
	s_and_saveexec_b64 s[2:3], vcc
	s_xor_b64 s[6:7], exec, s[2:3]
	s_cbranch_execz .LBB0_1009
	v_readlane_b32 s2, v252, 34
	v_lshlrev_b32_e32 v66, 11, v67
	s_nop 0
	v_add_u32_e32 v68, s2, v67
	v_readlane_b32 s2, v252, 54
	v_mul_hi_i32_i24_e32 v69, 0x6000, v68
	v_mul_i32_i24_e32 v68, 0x6000, v68
	v_add3_u32 v66, v66, s2, v72
.LBB0_1009:
	s_or_saveexec_b64 s[6:7], s[6:7]
	v_readlane_b32 s12, v252, 28
	v_readlane_b32 s14, v252, 30
	v_readlane_b32 s15, v252, 31
	v_readlane_b32 s13, v252, 29
	s_nop 0
	v_mov_b64_e32 v[70:71], s[14:15]
	s_xor_b64 exec, exec, s[6:7]
	v_lshl_add_u32 v66, v67, 8, v72
	v_mov_b64_e32 v[68:69], 0x60000
	v_mov_b64_e32 v[70:71], s[68:69]
	s_or_b64 exec, exec, s[6:7]
	v_ashrrev_i32_e32 v67, 31, v66
	v_lshlrev_b64 v[66:67], 12, v[66:67]
	v_lshl_add_u64 v[66:67], v[70:71], 0, v[66:67]
	v_lshl_add_u64 v[76:77], v[140:141], 0, v[68:69]
	v_lshl_add_u64 v[74:75], v[138:139], 2, v[66:67]
	global_load_dwordx4 v[202:205], v[76:77], off
	global_load_dwordx4 v[206:209], v[74:75], off
	global_load_dwordx4 v[210:213], v[76:77], off offset:64
	global_load_dwordx4 v[214:217], v[74:75], off offset:64
	global_load_dwordx4 v[218:221], v[76:77], off offset:128
	global_load_dwordx4 v[222:225], v[74:75], off offset:128
	global_load_dwordx4 v[226:229], v[76:77], off offset:192
	global_load_dwordx4 v[230:233], v[74:75], off offset:192
	s_mov_b32 s2, 0x38e38e39
	s_waitcnt vmcnt(0)
	v_pk_fma_f32 v[62:63], v[62:63], v[202:203], v[206:207]
	v_pk_fma_f32 v[64:65], v[64:65], v[204:205], v[208:209]
	v_pk_fma_f32 v[58:59], v[58:59], v[210:211], v[214:215]
	v_pk_fma_f32 v[60:61], v[60:61], v[212:213], v[216:217]
	v_pk_fma_f32 v[54:55], v[54:55], v[218:219], v[222:223]
	v_pk_fma_f32 v[56:57], v[56:57], v[220:221], v[224:225]
	v_pk_fma_f32 v[50:51], v[50:51], v[226:227], v[230:231]
	v_pk_fma_f32 v[52:53], v[52:53], v[228:229], v[232:233]
	global_store_dwordx4 v[74:75], v[62:65], off
	global_store_dwordx4 v[74:75], v[58:61], off offset:64
	global_store_dwordx4 v[74:75], v[54:57], off offset:128
	global_store_dwordx4 v[74:75], v[50:53], off offset:192
	s_nop 1
	v_or_b32_e32 v50, 0x50, v155
	v_mul_hi_i32 v51, v50, s2
	v_lshrrev_b32_e32 v52, 31, v51
	v_ashrrev_i32_e32 v51, 9, v51
	v_add_u32_e32 v51, v51, v52
	v_mad_i32_i24 v56, v51, s53, v50
	v_cmp_lt_i32_e32 vcc, s39, v56
	s_and_saveexec_b64 s[2:3], vcc
	s_xor_b64 s[6:7], exec, s[2:3]
	s_cbranch_execz .LBB0_1013
	v_readlane_b32 s2, v252, 34
	v_lshlrev_b32_e32 v50, 11, v51
	s_nop 0
	v_add_u32_e32 v52, s2, v51
	v_readlane_b32 s2, v252, 54
	v_mul_hi_i32_i24_e32 v53, 0x6000, v52
	v_mul_i32_i24_e32 v52, 0x6000, v52
	v_add3_u32 v50, v50, s2, v56
.LBB0_1013:
	s_or_saveexec_b64 s[6:7], s[6:7]
	v_readlane_b32 s12, v252, 28
	v_readlane_b32 s14, v252, 30
	v_readlane_b32 s15, v252, 31
	v_readlane_b32 s13, v252, 29
	s_nop 0
	v_mov_b64_e32 v[54:55], s[14:15]
	s_xor_b64 exec, exec, s[6:7]
	v_lshl_add_u32 v50, v51, 8, v56
	v_mov_b64_e32 v[52:53], 0x60000
	v_mov_b64_e32 v[54:55], s[68:69]
	s_or_b64 exec, exec, s[6:7]
	v_ashrrev_i32_e32 v51, 31, v50
	v_lshlrev_b64 v[50:51], 12, v[50:51]
	v_lshl_add_u64 v[50:51], v[54:55], 0, v[50:51]
	v_lshl_add_u64 v[60:61], v[140:141], 0, v[52:53]
	v_lshl_add_u64 v[58:59], v[138:139], 2, v[50:51]
	global_load_dwordx4 v[202:205], v[60:61], off
	global_load_dwordx4 v[206:209], v[58:59], off
	global_load_dwordx4 v[210:213], v[60:61], off offset:64
	global_load_dwordx4 v[214:217], v[58:59], off offset:64
	global_load_dwordx4 v[218:221], v[60:61], off offset:128
	global_load_dwordx4 v[222:225], v[58:59], off offset:128
	global_load_dwordx4 v[226:229], v[60:61], off offset:192
	global_load_dwordx4 v[230:233], v[58:59], off offset:192
	s_mov_b32 s2, 0x38e38e39
	s_waitcnt vmcnt(0)
	v_pk_fma_f32 v[46:47], v[46:47], v[202:203], v[206:207]
	v_pk_fma_f32 v[48:49], v[48:49], v[204:205], v[208:209]
	v_pk_fma_f32 v[42:43], v[42:43], v[210:211], v[214:215]
	v_pk_fma_f32 v[44:45], v[44:45], v[212:213], v[216:217]
	v_pk_fma_f32 v[38:39], v[38:39], v[218:219], v[222:223]
	v_pk_fma_f32 v[40:41], v[40:41], v[220:221], v[224:225]
	v_pk_fma_f32 v[34:35], v[34:35], v[226:227], v[230:231]
	v_pk_fma_f32 v[36:37], v[36:37], v[228:229], v[232:233]
	global_store_dwordx4 v[58:59], v[46:49], off
	global_store_dwordx4 v[58:59], v[42:45], off offset:64
	global_store_dwordx4 v[58:59], v[38:41], off offset:128
	global_store_dwordx4 v[58:59], v[34:37], off offset:192
	s_nop 1
	v_or_b32_e32 v34, 0x60, v155
	v_mul_hi_i32 v35, v34, s2
	v_lshrrev_b32_e32 v36, 31, v35
	v_ashrrev_i32_e32 v35, 9, v35
	v_add_u32_e32 v35, v35, v36
	v_mad_i32_i24 v40, v35, s53, v34
	v_cmp_lt_i32_e32 vcc, s39, v40
	s_and_saveexec_b64 s[2:3], vcc
	s_xor_b64 s[6:7], exec, s[2:3]
	s_cbranch_execz .LBB0_1017
	v_readlane_b32 s2, v252, 34
	v_lshlrev_b32_e32 v34, 11, v35
	s_nop 0
	v_add_u32_e32 v36, s2, v35
	v_readlane_b32 s2, v252, 54
	v_mul_hi_i32_i24_e32 v37, 0x6000, v36
	v_mul_i32_i24_e32 v36, 0x6000, v36
	v_add3_u32 v34, v34, s2, v40
.LBB0_1017:
	s_or_saveexec_b64 s[6:7], s[6:7]
	v_readlane_b32 s12, v252, 28
	v_readlane_b32 s14, v252, 30
	v_readlane_b32 s15, v252, 31
	v_readlane_b32 s13, v252, 29
	s_nop 0
	v_mov_b64_e32 v[38:39], s[14:15]
	s_xor_b64 exec, exec, s[6:7]
	v_lshl_add_u32 v34, v35, 8, v40
	v_mov_b64_e32 v[36:37], 0x60000
	v_mov_b64_e32 v[38:39], s[68:69]
	s_or_b64 exec, exec, s[6:7]
	v_ashrrev_i32_e32 v35, 31, v34
	v_lshlrev_b64 v[34:35], 12, v[34:35]
	v_lshl_add_u64 v[34:35], v[38:39], 0, v[34:35]
	v_lshl_add_u64 v[44:45], v[140:141], 0, v[36:37]
	v_lshl_add_u64 v[42:43], v[138:139], 2, v[34:35]
	global_load_dwordx4 v[202:205], v[44:45], off
	global_load_dwordx4 v[206:209], v[42:43], off
	global_load_dwordx4 v[210:213], v[44:45], off offset:64
	global_load_dwordx4 v[214:217], v[42:43], off offset:64
	global_load_dwordx4 v[218:221], v[44:45], off offset:128
	global_load_dwordx4 v[222:225], v[42:43], off offset:128
	global_load_dwordx4 v[226:229], v[44:45], off offset:192
	global_load_dwordx4 v[230:233], v[42:43], off offset:192
	s_mov_b32 s2, 0x38e38e39
	s_waitcnt vmcnt(0)
	v_pk_fma_f32 v[30:31], v[30:31], v[202:203], v[206:207]
	v_pk_fma_f32 v[32:33], v[32:33], v[204:205], v[208:209]
	v_pk_fma_f32 v[26:27], v[26:27], v[210:211], v[214:215]
	v_pk_fma_f32 v[28:29], v[28:29], v[212:213], v[216:217]
	v_pk_fma_f32 v[22:23], v[22:23], v[218:219], v[222:223]
	v_pk_fma_f32 v[24:25], v[24:25], v[220:221], v[224:225]
	v_pk_fma_f32 v[18:19], v[18:19], v[226:227], v[230:231]
	v_pk_fma_f32 v[20:21], v[20:21], v[228:229], v[232:233]
	global_store_dwordx4 v[42:43], v[30:33], off
	global_store_dwordx4 v[42:43], v[26:29], off offset:64
	global_store_dwordx4 v[42:43], v[22:25], off offset:128
	global_store_dwordx4 v[42:43], v[18:21], off offset:192
	s_nop 1
	v_or_b32_e32 v18, 0x70, v155
	v_mul_hi_i32 v19, v18, s2
	v_lshrrev_b32_e32 v20, 31, v19
	v_ashrrev_i32_e32 v19, 9, v19
	v_add_u32_e32 v19, v19, v20
	v_mad_i32_i24 v24, v19, s53, v18
	v_cmp_lt_i32_e32 vcc, s39, v24
	s_and_saveexec_b64 s[2:3], vcc
	s_xor_b64 s[6:7], exec, s[2:3]
	s_cbranch_execz .LBB0_1021
	v_readlane_b32 s2, v252, 34
	v_lshlrev_b32_e32 v18, 11, v19
	s_nop 0
	v_add_u32_e32 v20, s2, v19
	v_readlane_b32 s2, v252, 54
	v_mul_hi_i32_i24_e32 v21, 0x6000, v20
	v_mul_i32_i24_e32 v20, 0x6000, v20
	v_add3_u32 v18, v18, s2, v24

.LBB0_1200:
	s_or_b64 exec, exec, s[6:7]
	v_ashrrev_i32_e32 v19, 31, v18
	v_lshlrev_b64 v[18:19], 12, v[18:19]
	v_lshl_add_u64 v[18:19], v[22:23], 0, v[18:19]
	v_lshl_add_u64 v[28:29], v[68:69], 0, v[20:21]
	v_lshl_add_u64 v[26:27], v[66:67], 2, v[18:19]
	global_load_dwordx4 v[202:205], v[28:29], off
	global_load_dwordx4 v[206:209], v[26:27], off
	global_load_dwordx4 v[210:213], v[28:29], off offset:64
	global_load_dwordx4 v[214:217], v[26:27], off offset:64
	global_load_dwordx4 v[218:221], v[28:29], off offset:128
	global_load_dwordx4 v[222:225], v[26:27], off offset:128
	global_load_dwordx4 v[226:229], v[28:29], off offset:192
	global_load_dwordx4 v[230:233], v[26:27], off offset:192
	s_waitcnt vmcnt(0)
	v_pk_fma_f32 v[14:15], v[14:15], v[202:203], v[206:207]
	v_pk_fma_f32 v[16:17], v[16:17], v[204:205], v[208:209]
	v_pk_fma_f32 v[10:11], v[10:11], v[210:211], v[214:215]
	v_pk_fma_f32 v[12:13], v[12:13], v[212:213], v[216:217]
	v_pk_fma_f32 v[6:7], v[6:7], v[218:219], v[222:223]
	v_pk_fma_f32 v[8:9], v[8:9], v[220:221], v[224:225]
	v_pk_fma_f32 v[2:3], v[2:3], v[226:227], v[230:231]
	v_pk_fma_f32 v[4:5], v[4:5], v[228:229], v[232:233]
	global_store_dwordx4 v[26:27], v[14:17], off
	global_store_dwordx4 v[26:27], v[10:13], off offset:64
	global_store_dwordx4 v[26:27], v[6:9], off offset:128
	global_store_dwordx4 v[26:27], v[2:5], off offset:192

.LBB0_1219:
	s_or_saveexec_b64 s[12:13], s[12:13]
	v_readlane_b32 s28, v252, 28
	v_readlane_b32 s30, v252, 30
	v_readlane_b32 s31, v252, 31
	v_readlane_b32 s29, v252, 29
	s_nop 0
	v_mov_b64_e32 v[74:75], s[30:31]
	s_xor_b64 exec, exec, s[12:13]
	v_lshl_add_u32 v70, v66, 8, v67
	v_mov_b64_e32 v[72:73], 0x60000
	v_mov_b64_e32 v[74:75], s[68:69]
	s_or_b64 exec, exec, s[12:13]
	v_or_b32_e32 v66, s6, v114
	v_ashrrev_i32_e32 v67, 31, v66
	v_lshlrev_b64 v[78:79], 2, v[66:67]
	v_ashrrev_i32_e32 v71, 31, v70
	v_lshl_add_u64 v[68:69], s[38:39], 0, v[78:79]
	v_lshlrev_b64 v[70:71], 12, v[70:71]
	v_lshl_add_u64 v[70:71], v[74:75], 0, v[70:71]
	v_lshl_add_u64 v[82:83], v[68:69], 0, v[72:73]
	v_lshl_add_u64 v[74:75], v[70:71], 0, v[78:79]
	global_load_dwordx4 v[202:205], v[82:83], off
	global_load_dwordx4 v[206:209], v[74:75], off
	global_load_dwordx4 v[210:213], v[82:83], off offset:64
	global_load_dwordx4 v[214:217], v[74:75], off offset:64
	global_load_dwordx4 v[218:221], v[82:83], off offset:128
	global_load_dwordx4 v[222:225], v[74:75], off offset:128
	global_load_dwordx4 v[226:229], v[82:83], off offset:192
	global_load_dwordx4 v[230:233], v[74:75], off offset:192
	s_mov_b32 s2, 0x38e38e39
	s_waitcnt vmcnt(0)
	v_pk_fma_f32 v[62:63], v[62:63], v[202:203], v[206:207]
	v_pk_fma_f32 v[64:65], v[64:65], v[204:205], v[208:209]
	v_pk_fma_f32 v[58:59], v[58:59], v[210:211], v[214:215]
	v_pk_fma_f32 v[60:61], v[60:61], v[212:213], v[216:217]
	v_pk_fma_f32 v[54:55], v[54:55], v[218:219], v[222:223]
	v_pk_fma_f32 v[56:57], v[56:57], v[220:221], v[224:225]
	v_pk_fma_f32 v[50:51], v[50:51], v[226:227], v[230:231]
	v_pk_fma_f32 v[52:53], v[52:53], v[228:229], v[232:233]
	global_store_dwordx4 v[74:75], v[62:65], off
	global_store_dwordx4 v[74:75], v[58:61], off offset:64
	global_store_dwordx4 v[74:75], v[54:57], off offset:128
	global_store_dwordx4 v[74:75], v[50:53], off offset:192
	s_nop 1
	v_or_b32_e32 v50, 16, v76
	v_mul_hi_i32 v51, v50, s2
	v_lshrrev_b32_e32 v52, 31, v51
	v_ashrrev_i32_e32 v51, 9, v51
	v_add_u32_e32 v51, v51, v52
	v_mad_i32_i24 v56, v51, s53, v50
	v_cmp_lt_i32_e32 vcc, s18, v56
	s_and_saveexec_b64 s[2:3], vcc
	s_xor_b64 s[6:7], exec, s[2:3]
	s_cbranch_execz .LBB0_1223
	v_readlane_b32 s2, v252, 34
	v_lshlrev_b32_e32 v50, 11, v51
	s_nop 0
	v_add_u32_e32 v52, s2, v51
	v_readlane_b32 s2, v252, 54
	v_mul_hi_i32_i24_e32 v53, 0x6000, v52
	v_mul_i32_i24_e32 v52, 0x6000, v52
	v_add3_u32 v50, v50, s2, v56
.LBB0_1223:
	s_or_saveexec_b64 s[6:7], s[6:7]
	v_readlane_b32 s12, v252, 28
	v_readlane_b32 s14, v252, 30
	v_readlane_b32 s15, v252, 31
	v_readlane_b32 s13, v252, 29
	s_nop 0
	v_mov_b64_e32 v[54:55], s[14:15]
	s_xor_b64 exec, exec, s[6:7]
	v_lshl_add_u32 v50, v51, 8, v56
	v_mov_b64_e32 v[52:53], 0x60000
	v_mov_b64_e32 v[54:55], s[68:69]
	s_or_b64 exec, exec, s[6:7]
	v_ashrrev_i32_e32 v51, 31, v50
	v_lshlrev_b64 v[50:51], 12, v[50:51]
	v_lshl_add_u64 v[50:51], v[54:55], 0, v[50:51]
	v_lshl_add_u64 v[60:61], v[68:69], 0, v[52:53]
	v_lshl_add_u64 v[58:59], v[66:67], 2, v[50:51]
	global_load_dwordx4 v[202:205], v[60:61], off
	global_load_dwordx4 v[206:209], v[58:59], off
	global_load_dwordx4 v[210:213], v[60:61], off offset:64
	global_load_dwordx4 v[214:217], v[58:59], off offset:64
	global_load_dwordx4 v[218:221], v[60:61], off offset:128
	global_load_dwordx4 v[222:225], v[58:59], off offset:128
	global_load_dwordx4 v[226:229], v[60:61], off offset:192
	global_load_dwordx4 v[230:233], v[58:59], off offset:192
	s_mov_b32 s2, 0x38e38e39
	s_waitcnt vmcnt(0)
	v_pk_fma_f32 v[46:47], v[46:47], v[202:203], v[206:207]
	v_pk_fma_f32 v[48:49], v[48:49], v[204:205], v[208:209]
	v_pk_fma_f32 v[42:43], v[42:43], v[210:211], v[214:215]
	v_pk_fma_f32 v[44:45], v[44:45], v[212:213], v[216:217]
	v_pk_fma_f32 v[38:39], v[38:39], v[218:219], v[222:223]
	v_pk_fma_f32 v[40:41], v[40:41], v[220:221], v[224:225]
	v_pk_fma_f32 v[34:35], v[34:35], v[226:227], v[230:231]
	v_pk_fma_f32 v[36:37], v[36:37], v[228:229], v[232:233]
	global_store_dwordx4 v[58:59], v[46:49], off
	global_store_dwordx4 v[58:59], v[42:45], off offset:64
	global_store_dwordx4 v[58:59], v[38:41], off offset:128
	global_store_dwordx4 v[58:59], v[34:37], off offset:192
	s_nop 1
	v_or_b32_e32 v34, 32, v76
	v_mul_hi_i32 v35, v34, s2
	v_lshrrev_b32_e32 v36, 31, v35
	v_ashrrev_i32_e32 v35, 9, v35
	v_add_u32_e32 v35, v35, v36
	v_mad_i32_i24 v40, v35, s53, v34
	v_cmp_lt_i32_e32 vcc, s18, v40
	s_and_saveexec_b64 s[2:3], vcc
	s_xor_b64 s[6:7], exec, s[2:3]
	s_cbranch_execz .LBB0_1227
	v_readlane_b32 s2, v252, 34
	v_lshlrev_b32_e32 v34, 11, v35
	s_nop 0
	v_add_u32_e32 v36, s2, v35
	v_readlane_b32 s2, v252, 54
	v_mul_hi_i32_i24_e32 v37, 0x6000, v36
	v_mul_i32_i24_e32 v36, 0x6000, v36
	v_add3_u32 v34, v34, s2, v40
.LBB0_1227:
	s_or_saveexec_b64 s[6:7], s[6:7]
	v_readlane_b32 s12, v252, 28
	v_readlane_b32 s14, v252, 30
	v_readlane_b32 s15, v252, 31
	v_readlane_b32 s13, v252, 29
	s_nop 0
	v_mov_b64_e32 v[38:39], s[14:15]
	s_xor_b64 exec, exec, s[6:7]
	v_lshl_add_u32 v34, v35, 8, v40
	v_mov_b64_e32 v[36:37], 0x60000
	v_mov_b64_e32 v[38:39], s[68:69]
	s_or_b64 exec, exec, s[6:7]
	v_ashrrev_i32_e32 v35, 31, v34
	v_lshlrev_b64 v[34:35], 12, v[34:35]
	v_lshl_add_u64 v[34:35], v[38:39], 0, v[34:35]
	v_lshl_add_u64 v[44:45], v[68:69], 0, v[36:37]
	v_lshl_add_u64 v[42:43], v[66:67], 2, v[34:35]
	global_load_dwordx4 v[202:205], v[44:45], off
	global_load_dwordx4 v[206:209], v[42:43], off
	global_load_dwordx4 v[210:213], v[44:45], off offset:64
	global_load_dwordx4 v[214:217], v[42:43], off offset:64
	global_load_dwordx4 v[218:221], v[44:45], off offset:128
	global_load_dwordx4 v[222:225], v[42:43], off offset:128
	global_load_dwordx4 v[226:229], v[44:45], off offset:192
	global_load_dwordx4 v[230:233], v[42:43], off offset:192
	s_mov_b32 s2, 0x38e38e39
	s_waitcnt vmcnt(0)
	v_pk_fma_f32 v[30:31], v[30:31], v[202:203], v[206:207]
	v_pk_fma_f32 v[32:33], v[32:33], v[204:205], v[208:209]
	v_pk_fma_f32 v[26:27], v[26:27], v[210:211], v[214:215]
	v_pk_fma_f32 v[28:29], v[28:29], v[212:213], v[216:217]
	v_pk_fma_f32 v[22:23], v[22:23], v[218:219], v[222:223]
	v_pk_fma_f32 v[24:25], v[24:25], v[220:221], v[224:225]
	v_pk_fma_f32 v[18:19], v[18:19], v[226:227], v[230:231]
	v_pk_fma_f32 v[20:21], v[20:21], v[228:229], v[232:233]
	global_store_dwordx4 v[42:43], v[30:33], off
	global_store_dwordx4 v[42:43], v[26:29], off offset:64
	global_store_dwordx4 v[42:43], v[22:25], off offset:128
	global_store_dwordx4 v[42:43], v[18:21], off offset:192
	s_nop 1
	v_or_b32_e32 v18, 48, v76
	v_mul_hi_i32 v19, v18, s2
	v_lshrrev_b32_e32 v20, 31, v19
	v_ashrrev_i32_e32 v19, 9, v19
	v_add_u32_e32 v19, v19, v20
	v_mad_i32_i24 v24, v19, s53, v18
	v_cmp_lt_i32_e32 vcc, s18, v24
	s_and_saveexec_b64 s[2:3], vcc
	s_xor_b64 s[6:7], exec, s[2:3]
	s_cbranch_execz .LBB0_1231
	v_readlane_b32 s2, v252, 34
	v_lshlrev_b32_e32 v18, 11, v19
	s_nop 0
	v_add_u32_e32 v20, s2, v19
	v_readlane_b32 s2, v252, 54
	v_mul_hi_i32_i24_e32 v21, 0x6000, v20
	v_mul_i32_i24_e32 v20, 0x6000, v20
	v_add3_u32 v18, v18, s2, v24

.LBB0_1246:
	s_or_saveexec_b64 s[6:7], s[6:7]
	v_readlane_b32 s28, v252, 28
	v_readlane_b32 s30, v252, 30
	v_readlane_b32 s31, v252, 31
	v_readlane_b32 s29, v252, 29
	s_nop 0
	v_mov_b64_e32 v[146:147], s[30:31]
	s_xor_b64 exec, exec, s[6:7]
	v_lshl_add_u32 v142, v138, 8, v139
	v_mov_b64_e32 v[144:145], 0x60000
	v_mov_b64_e32 v[146:147], s[68:69]
	s_or_b64 exec, exec, s[6:7]
	v_or_b32_e32 v138, s26, v152
	v_ashrrev_i32_e32 v139, 31, v138
	v_lshlrev_b64 v[154:155], 2, v[138:139]
	v_ashrrev_i32_e32 v143, 31, v142
	v_lshl_add_u64 v[140:141], s[38:39], 0, v[154:155]
	v_lshlrev_b64 v[142:143], 12, v[142:143]
	v_lshl_add_u64 v[142:143], v[146:147], 0, v[142:143]
	v_lshl_add_u64 v[158:159], v[140:141], 0, v[144:145]
	v_lshl_add_u64 v[146:147], v[142:143], 0, v[154:155]
	global_load_dwordx4 v[202:205], v[158:159], off
	global_load_dwordx4 v[206:209], v[146:147], off
	global_load_dwordx4 v[210:213], v[158:159], off offset:64
	global_load_dwordx4 v[214:217], v[146:147], off offset:64
	global_load_dwordx4 v[218:221], v[158:159], off offset:128
	global_load_dwordx4 v[222:225], v[146:147], off offset:128
	global_load_dwordx4 v[226:229], v[158:159], off offset:192
	global_load_dwordx4 v[230:233], v[146:147], off offset:192
	s_mov_b32 s2, 0x38e38e39
	s_waitcnt vmcnt(0)
	v_pk_fma_f32 v[126:127], v[126:127], v[202:203], v[206:207]
	v_pk_fma_f32 v[128:129], v[128:129], v[204:205], v[208:209]
	v_pk_fma_f32 v[122:123], v[122:123], v[210:211], v[214:215]
	v_pk_fma_f32 v[124:125], v[124:125], v[212:213], v[216:217]
	v_pk_fma_f32 v[118:119], v[118:119], v[218:219], v[222:223]
	v_pk_fma_f32 v[120:121], v[120:121], v[220:221], v[224:225]
	v_pk_fma_f32 v[114:115], v[114:115], v[226:227], v[230:231]
	v_pk_fma_f32 v[116:117], v[116:117], v[228:229], v[232:233]
	global_store_dwordx4 v[146:147], v[126:129], off
	global_store_dwordx4 v[146:147], v[122:125], off offset:64
	global_store_dwordx4 v[146:147], v[118:121], off offset:128
	global_store_dwordx4 v[146:147], v[114:117], off offset:192
	s_nop 1
	v_or_b32_e32 v114, 16, v153
	v_mul_hi_i32 v115, v114, s2
	v_lshrrev_b32_e32 v116, 31, v115
	v_ashrrev_i32_e32 v115, 9, v115
	v_add_u32_e32 v115, v115, v116
	v_mad_i32_i24 v120, v115, s53, v114
	v_cmp_lt_i32_e32 vcc, s12, v120
	s_and_saveexec_b64 s[2:3], vcc
	s_xor_b64 s[6:7], exec, s[2:3]
	s_cbranch_execz .LBB0_1250
	v_readlane_b32 s2, v252, 34
	v_lshlrev_b32_e32 v114, 11, v115
	s_nop 0
	v_add_u32_e32 v116, s2, v115
	v_readlane_b32 s2, v252, 54
	v_mul_hi_i32_i24_e32 v117, 0x6000, v116
	v_mul_i32_i24_e32 v116, 0x6000, v116
	v_add3_u32 v114, v114, s2, v120
.LBB0_1250:
	s_or_saveexec_b64 s[6:7], s[6:7]
	v_readlane_b32 s28, v252, 28
	v_readlane_b32 s30, v252, 30
	v_readlane_b32 s31, v252, 31
	v_readlane_b32 s29, v252, 29
	s_nop 0
	v_mov_b64_e32 v[118:119], s[30:31]
	s_xor_b64 exec, exec, s[6:7]
	v_lshl_add_u32 v114, v115, 8, v120
	v_mov_b64_e32 v[116:117], 0x60000
	v_mov_b64_e32 v[118:119], s[68:69]
	s_or_b64 exec, exec, s[6:7]
	v_ashrrev_i32_e32 v115, 31, v114
	v_lshlrev_b64 v[114:115], 12, v[114:115]
	v_lshl_add_u64 v[114:115], v[118:119], 0, v[114:115]
	v_lshl_add_u64 v[124:125], v[140:141], 0, v[116:117]
	v_lshl_add_u64 v[122:123], v[138:139], 2, v[114:115]
	global_load_dwordx4 v[202:205], v[124:125], off
	global_load_dwordx4 v[206:209], v[122:123], off
	global_load_dwordx4 v[210:213], v[124:125], off offset:64
	global_load_dwordx4 v[214:217], v[122:123], off offset:64
	global_load_dwordx4 v[218:221], v[124:125], off offset:128
	global_load_dwordx4 v[222:225], v[122:123], off offset:128
	global_load_dwordx4 v[226:229], v[124:125], off offset:192
	global_load_dwordx4 v[230:233], v[122:123], off offset:192
	s_mov_b32 s2, 0x38e38e39
	s_waitcnt vmcnt(0)
	v_pk_fma_f32 v[110:111], v[110:111], v[202:203], v[206:207]
	v_pk_fma_f32 v[112:113], v[112:113], v[204:205], v[208:209]
	v_pk_fma_f32 v[106:107], v[106:107], v[210:211], v[214:215]
	v_pk_fma_f32 v[108:109], v[108:109], v[212:213], v[216:217]
	v_pk_fma_f32 v[102:103], v[102:103], v[218:219], v[222:223]
	v_pk_fma_f32 v[104:105], v[104:105], v[220:221], v[224:225]
	v_pk_fma_f32 v[98:99], v[98:99], v[226:227], v[230:231]
	v_pk_fma_f32 v[100:101], v[100:101], v[228:229], v[232:233]
	global_store_dwordx4 v[122:123], v[110:113], off
	global_store_dwordx4 v[122:123], v[106:109], off offset:64
	global_store_dwordx4 v[122:123], v[102:105], off offset:128
	global_store_dwordx4 v[122:123], v[98:101], off offset:192
	s_nop 1
	v_or_b32_e32 v98, 32, v153
	v_mul_hi_i32 v99, v98, s2
	v_lshrrev_b32_e32 v100, 31, v99
	v_ashrrev_i32_e32 v99, 9, v99
	v_add_u32_e32 v99, v99, v100
	v_mad_i32_i24 v104, v99, s53, v98
	v_cmp_lt_i32_e32 vcc, s12, v104
	s_and_saveexec_b64 s[2:3], vcc
	s_xor_b64 s[6:7], exec, s[2:3]
	s_cbranch_execz .LBB0_1254
	v_readlane_b32 s2, v252, 34
	v_lshlrev_b32_e32 v98, 11, v99
	s_nop 0
	v_add_u32_e32 v100, s2, v99
	v_readlane_b32 s2, v252, 54
	v_mul_hi_i32_i24_e32 v101, 0x6000, v100
	v_mul_i32_i24_e32 v100, 0x6000, v100
	v_add3_u32 v98, v98, s2, v104
.LBB0_1254:
	s_or_saveexec_b64 s[6:7], s[6:7]
	v_readlane_b32 s28, v252, 28
	v_readlane_b32 s30, v252, 30
	v_readlane_b32 s31, v252, 31
	v_readlane_b32 s29, v252, 29
	s_nop 0
	v_mov_b64_e32 v[102:103], s[30:31]
	s_xor_b64 exec, exec, s[6:7]
	v_lshl_add_u32 v98, v99, 8, v104
	v_mov_b64_e32 v[100:101], 0x60000
	v_mov_b64_e32 v[102:103], s[68:69]
	s_or_b64 exec, exec, s[6:7]
	v_ashrrev_i32_e32 v99, 31, v98
	v_lshlrev_b64 v[98:99], 12, v[98:99]
	v_lshl_add_u64 v[98:99], v[102:103], 0, v[98:99]
	v_lshl_add_u64 v[108:109], v[140:141], 0, v[100:101]
	v_lshl_add_u64 v[106:107], v[138:139], 2, v[98:99]
	global_load_dwordx4 v[202:205], v[108:109], off
	global_load_dwordx4 v[206:209], v[106:107], off
	global_load_dwordx4 v[210:213], v[108:109], off offset:64
	global_load_dwordx4 v[214:217], v[106:107], off offset:64
	global_load_dwordx4 v[218:221], v[108:109], off offset:128
	global_load_dwordx4 v[222:225], v[106:107], off offset:128
	global_load_dwordx4 v[226:229], v[108:109], off offset:192
	global_load_dwordx4 v[230:233], v[106:107], off offset:192
	s_mov_b32 s2, 0x38e38e39
	s_waitcnt vmcnt(0)
	v_pk_fma_f32 v[94:95], v[94:95], v[202:203], v[206:207]
	v_pk_fma_f32 v[96:97], v[96:97], v[204:205], v[208:209]
	v_pk_fma_f32 v[90:91], v[90:91], v[210:211], v[214:215]
	v_pk_fma_f32 v[92:93], v[92:93], v[212:213], v[216:217]
	v_pk_fma_f32 v[86:87], v[86:87], v[218:219], v[222:223]
	v_pk_fma_f32 v[88:89], v[88:89], v[220:221], v[224:225]
	v_pk_fma_f32 v[82:83], v[82:83], v[226:227], v[230:231]
	v_pk_fma_f32 v[84:85], v[84:85], v[228:229], v[232:233]
	global_store_dwordx4 v[106:107], v[94:97], off
	global_store_dwordx4 v[106:107], v[90:93], off offset:64
	global_store_dwordx4 v[106:107], v[86:89], off offset:128
	global_store_dwordx4 v[106:107], v[82:85], off offset:192
	s_nop 1
	v_or_b32_e32 v82, 48, v153
	v_mul_hi_i32 v83, v82, s2
	v_lshrrev_b32_e32 v84, 31, v83
	v_ashrrev_i32_e32 v83, 9, v83
	v_add_u32_e32 v83, v83, v84
	v_mad_i32_i24 v88, v83, s53, v82
	v_cmp_lt_i32_e32 vcc, s12, v88
	s_and_saveexec_b64 s[2:3], vcc
	s_xor_b64 s[6:7], exec, s[2:3]
	s_cbranch_execz .LBB0_1258
	v_readlane_b32 s2, v252, 34
	v_lshlrev_b32_e32 v82, 11, v83
	s_nop 0
	v_add_u32_e32 v84, s2, v83
	v_readlane_b32 s2, v252, 54
	v_mul_hi_i32_i24_e32 v85, 0x6000, v84
	v_mul_i32_i24_e32 v84, 0x6000, v84
	v_add3_u32 v82, v82, s2, v88
.LBB0_1258:
	s_or_saveexec_b64 s[6:7], s[6:7]
	v_readlane_b32 s28, v252, 28
	v_readlane_b32 s30, v252, 30
	v_readlane_b32 s31, v252, 31
	v_readlane_b32 s29, v252, 29
	s_nop 0
	v_mov_b64_e32 v[86:87], s[30:31]
	s_xor_b64 exec, exec, s[6:7]
	v_lshl_add_u32 v82, v83, 8, v88
	v_mov_b64_e32 v[84:85], 0x60000
	v_mov_b64_e32 v[86:87], s[68:69]
	s_or_b64 exec, exec, s[6:7]
	v_ashrrev_i32_e32 v83, 31, v82
	v_lshlrev_b64 v[82:83], 12, v[82:83]
	v_lshl_add_u64 v[82:83], v[86:87], 0, v[82:83]
	v_lshl_add_u64 v[92:93], v[140:141], 0, v[84:85]
	v_lshl_add_u64 v[90:91], v[138:139], 2, v[82:83]
	global_load_dwordx4 v[202:205], v[92:93], off
	global_load_dwordx4 v[206:209], v[90:91], off
	global_load_dwordx4 v[210:213], v[92:93], off offset:64
	global_load_dwordx4 v[214:217], v[90:91], off offset:64
	global_load_dwordx4 v[218:221], v[92:93], off offset:128
	global_load_dwordx4 v[222:225], v[90:91], off offset:128
	global_load_dwordx4 v[226:229], v[92:93], off offset:192
	global_load_dwordx4 v[230:233], v[90:91], off offset:192
	s_mov_b32 s2, 0x38e38e39
	s_waitcnt vmcnt(0)
	v_pk_fma_f32 v[78:79], v[78:79], v[202:203], v[206:207]
	v_pk_fma_f32 v[80:81], v[80:81], v[204:205], v[208:209]
	v_pk_fma_f32 v[74:75], v[74:75], v[210:211], v[214:215]
	v_pk_fma_f32 v[76:77], v[76:77], v[212:213], v[216:217]
	v_pk_fma_f32 v[70:71], v[70:71], v[218:219], v[222:223]
	v_pk_fma_f32 v[72:73], v[72:73], v[220:221], v[224:225]
	v_pk_fma_f32 v[66:67], v[66:67], v[226:227], v[230:231]
	v_pk_fma_f32 v[68:69], v[68:69], v[228:229], v[232:233]
	global_store_dwordx4 v[90:91], v[78:81], off
	global_store_dwordx4 v[90:91], v[74:77], off offset:64
	global_store_dwordx4 v[90:91], v[70:73], off offset:128
	global_store_dwordx4 v[90:91], v[66:69], off offset:192
	s_nop 1
	v_or_b32_e32 v66, 64, v153
	v_mul_hi_i32 v67, v66, s2
	v_lshrrev_b32_e32 v68, 31, v67
	v_ashrrev_i32_e32 v67, 9, v67
	v_add_u32_e32 v67, v67, v68
	v_mad_i32_i24 v72, v67, s53, v66
	v_cmp_lt_i32_e32 vcc, s12, v72
	s_and_saveexec_b64 s[2:3], vcc
	s_xor_b64 s[6:7], exec, s[2:3]
	s_cbranch_execz .LBB0_1262
	v_readlane_b32 s2, v252, 34
	v_lshlrev_b32_e32 v66, 11, v67
	s_nop 0
	v_add_u32_e32 v68, s2, v67
	v_readlane_b32 s2, v252, 54
	v_mul_hi_i32_i24_e32 v69, 0x6000, v68
	v_mul_i32_i24_e32 v68, 0x6000, v68
	v_add3_u32 v66, v66, s2, v72
.LBB0_1262:
	s_or_saveexec_b64 s[6:7], s[6:7]
	v_readlane_b32 s28, v252, 28
	v_readlane_b32 s30, v252, 30
	v_readlane_b32 s31, v252, 31
	v_readlane_b32 s29, v252, 29
	s_nop 0
	v_mov_b64_e32 v[70:71], s[30:31]
	s_xor_b64 exec, exec, s[6:7]
	v_lshl_add_u32 v66, v67, 8, v72
	v_mov_b64_e32 v[68:69], 0x60000
	v_mov_b64_e32 v[70:71], s[68:69]
	s_or_b64 exec, exec, s[6:7]
	v_ashrrev_i32_e32 v67, 31, v66
	v_lshlrev_b64 v[66:67], 12, v[66:67]
	v_lshl_add_u64 v[66:67], v[70:71], 0, v[66:67]
	v_lshl_add_u64 v[76:77], v[140:141], 0, v[68:69]
	v_lshl_add_u64 v[74:75], v[138:139], 2, v[66:67]
	global_load_dwordx4 v[202:205], v[76:77], off
	global_load_dwordx4 v[206:209], v[74:75], off
	global_load_dwordx4 v[210:213], v[76:77], off offset:64
	global_load_dwordx4 v[214:217], v[74:75], off offset:64
	global_load_dwordx4 v[218:221], v[76:77], off offset:128
	global_load_dwordx4 v[222:225], v[74:75], off offset:128
	global_load_dwordx4 v[226:229], v[76:77], off offset:192
	global_load_dwordx4 v[230:233], v[74:75], off offset:192
	s_mov_b32 s2, 0x38e38e39
	s_waitcnt vmcnt(0)
	v_pk_fma_f32 v[62:63], v[62:63], v[202:203], v[206:207]
	v_pk_fma_f32 v[64:65], v[64:65], v[204:205], v[208:209]
	v_pk_fma_f32 v[58:59], v[58:59], v[210:211], v[214:215]
	v_pk_fma_f32 v[60:61], v[60:61], v[212:213], v[216:217]
	v_pk_fma_f32 v[54:55], v[54:55], v[218:219], v[222:223]
	v_pk_fma_f32 v[56:57], v[56:57], v[220:221], v[224:225]
	v_pk_fma_f32 v[50:51], v[50:51], v[226:227], v[230:231]
	v_pk_fma_f32 v[52:53], v[52:53], v[228:229], v[232:233]
	global_store_dwordx4 v[74:75], v[62:65], off
	global_store_dwordx4 v[74:75], v[58:61], off offset:64
	global_store_dwordx4 v[74:75], v[54:57], off offset:128
	global_store_dwordx4 v[74:75], v[50:53], off offset:192
	s_nop 1
	v_or_b32_e32 v50, 0x50, v153
	v_mul_hi_i32 v51, v50, s2
	v_lshrrev_b32_e32 v52, 31, v51
	v_ashrrev_i32_e32 v51, 9, v51
	v_add_u32_e32 v51, v51, v52
	v_mad_i32_i24 v56, v51, s53, v50
	v_cmp_lt_i32_e32 vcc, s12, v56
	s_and_saveexec_b64 s[2:3], vcc
	s_xor_b64 s[6:7], exec, s[2:3]
	s_cbranch_execz .LBB0_1266
	v_readlane_b32 s2, v252, 34
	v_lshlrev_b32_e32 v50, 11, v51
	s_nop 0
	v_add_u32_e32 v52, s2, v51
	v_readlane_b32 s2, v252, 54
	v_mul_hi_i32_i24_e32 v53, 0x6000, v52
	v_mul_i32_i24_e32 v52, 0x6000, v52
	v_add3_u32 v50, v50, s2, v56
.LBB0_1266:
	s_or_saveexec_b64 s[6:7], s[6:7]
	v_readlane_b32 s28, v252, 28
	v_readlane_b32 s30, v252, 30
	v_readlane_b32 s31, v252, 31
	v_readlane_b32 s29, v252, 29
	s_nop 0
	v_mov_b64_e32 v[54:55], s[30:31]
	s_xor_b64 exec, exec, s[6:7]
	v_lshl_add_u32 v50, v51, 8, v56
	v_mov_b64_e32 v[52:53], 0x60000
	v_mov_b64_e32 v[54:55], s[68:69]
	s_or_b64 exec, exec, s[6:7]
	v_ashrrev_i32_e32 v51, 31, v50
	v_lshlrev_b64 v[50:51], 12, v[50:51]
	v_lshl_add_u64 v[50:51], v[54:55], 0, v[50:51]
	v_lshl_add_u64 v[60:61], v[140:141], 0, v[52:53]
	v_lshl_add_u64 v[58:59], v[138:139], 2, v[50:51]
	global_load_dwordx4 v[202:205], v[60:61], off
	global_load_dwordx4 v[206:209], v[58:59], off
	global_load_dwordx4 v[210:213], v[60:61], off offset:64
	global_load_dwordx4 v[214:217], v[58:59], off offset:64
	global_load_dwordx4 v[218:221], v[60:61], off offset:128
	global_load_dwordx4 v[222:225], v[58:59], off offset:128
	global_load_dwordx4 v[226:229], v[60:61], off offset:192
	global_load_dwordx4 v[230:233], v[58:59], off offset:192
	s_mov_b32 s2, 0x38e38e39
	s_waitcnt vmcnt(0)
	v_pk_fma_f32 v[46:47], v[46:47], v[202:203], v[206:207]
	v_pk_fma_f32 v[48:49], v[48:49], v[204:205], v[208:209]
	v_pk_fma_f32 v[42:43], v[42:43], v[210:211], v[214:215]
	v_pk_fma_f32 v[44:45], v[44:45], v[212:213], v[216:217]
	v_pk_fma_f32 v[38:39], v[38:39], v[218:219], v[222:223]
	v_pk_fma_f32 v[40:41], v[40:41], v[220:221], v[224:225]
	v_pk_fma_f32 v[34:35], v[34:35], v[226:227], v[230:231]
	v_pk_fma_f32 v[36:37], v[36:37], v[228:229], v[232:233]
	global_store_dwordx4 v[58:59], v[46:49], off
	global_store_dwordx4 v[58:59], v[42:45], off offset:64
	global_store_dwordx4 v[58:59], v[38:41], off offset:128
	global_store_dwordx4 v[58:59], v[34:37], off offset:192
	s_nop 1
	v_or_b32_e32 v34, 0x60, v153
	v_mul_hi_i32 v35, v34, s2
	v_lshrrev_b32_e32 v36, 31, v35
	v_ashrrev_i32_e32 v35, 9, v35
	v_add_u32_e32 v35, v35, v36
	v_mad_i32_i24 v40, v35, s53, v34
	v_cmp_lt_i32_e32 vcc, s12, v40
	s_and_saveexec_b64 s[2:3], vcc
	s_xor_b64 s[6:7], exec, s[2:3]
	s_cbranch_execz .LBB0_1270
	v_readlane_b32 s2, v252, 34
	v_lshlrev_b32_e32 v34, 11, v35
	s_nop 0
	v_add_u32_e32 v36, s2, v35
	v_readlane_b32 s2, v252, 54
	v_mul_hi_i32_i24_e32 v37, 0x6000, v36
	v_mul_i32_i24_e32 v36, 0x6000, v36
	v_add3_u32 v34, v34, s2, v40
.LBB0_1270:
	s_or_saveexec_b64 s[6:7], s[6:7]
	v_readlane_b32 s28, v252, 28
	v_readlane_b32 s30, v252, 30
	v_readlane_b32 s31, v252, 31
	v_readlane_b32 s29, v252, 29
	s_nop 0
	v_mov_b64_e32 v[38:39], s[30:31]
	s_xor_b64 exec, exec, s[6:7]
	v_lshl_add_u32 v34, v35, 8, v40
	v_mov_b64_e32 v[36:37], 0x60000
	v_mov_b64_e32 v[38:39], s[68:69]
	s_or_b64 exec, exec, s[6:7]
	v_ashrrev_i32_e32 v35, 31, v34
	v_lshlrev_b64 v[34:35], 12, v[34:35]
	v_lshl_add_u64 v[34:35], v[38:39], 0, v[34:35]
	v_lshl_add_u64 v[44:45], v[140:141], 0, v[36:37]
	v_lshl_add_u64 v[42:43], v[138:139], 2, v[34:35]
	global_load_dwordx4 v[202:205], v[44:45], off
	global_load_dwordx4 v[206:209], v[42:43], off
	global_load_dwordx4 v[210:213], v[44:45], off offset:64
	global_load_dwordx4 v[214:217], v[42:43], off offset:64
	global_load_dwordx4 v[218:221], v[44:45], off offset:128
	global_load_dwordx4 v[222:225], v[42:43], off offset:128
	global_load_dwordx4 v[226:229], v[44:45], off offset:192
	global_load_dwordx4 v[230:233], v[42:43], off offset:192
	s_mov_b32 s2, 0x38e38e39
	s_waitcnt vmcnt(0)
	v_pk_fma_f32 v[30:31], v[30:31], v[202:203], v[206:207]
	v_pk_fma_f32 v[32:33], v[32:33], v[204:205], v[208:209]
	v_pk_fma_f32 v[26:27], v[26:27], v[210:211], v[214:215]
	v_pk_fma_f32 v[28:29], v[28:29], v[212:213], v[216:217]
	v_pk_fma_f32 v[22:23], v[22:23], v[218:219], v[222:223]
	v_pk_fma_f32 v[24:25], v[24:25], v[220:221], v[224:225]
	v_pk_fma_f32 v[18:19], v[18:19], v[226:227], v[230:231]
	v_pk_fma_f32 v[20:21], v[20:21], v[228:229], v[232:233]
	global_store_dwordx4 v[42:43], v[30:33], off
	global_store_dwordx4 v[42:43], v[26:29], off offset:64
	global_store_dwordx4 v[42:43], v[22:25], off offset:128
	global_store_dwordx4 v[42:43], v[18:21], off offset:192
	s_nop 1
	v_or_b32_e32 v18, 0x70, v153
	v_mul_hi_i32 v19, v18, s2
	v_lshrrev_b32_e32 v20, 31, v19
	v_ashrrev_i32_e32 v19, 9, v19
	v_add_u32_e32 v19, v19, v20
	v_mad_i32_i24 v24, v19, s53, v18
	v_cmp_lt_i32_e32 vcc, s12, v24
	s_and_saveexec_b64 s[2:3], vcc
	s_xor_b64 s[6:7], exec, s[2:3]
	s_cbranch_execz .LBB0_1274
	v_readlane_b32 s2, v252, 34
	v_lshlrev_b32_e32 v18, 11, v19
	s_nop 0
	v_add_u32_e32 v20, s2, v19
	v_readlane_b32 s2, v252, 54
	v_mul_hi_i32_i24_e32 v21, 0x6000, v20
	v_mul_i32_i24_e32 v20, 0x6000, v20
	v_add3_u32 v18, v18, s2, v24
